# GEMM K-loops: s_setprio 1 before the opening barrier / s_setprio 0 after the closing barrier of each MFMA phase (phase = MFMAs only)
# speedup vs baseline: 1.0115x; 1.0060x over previous
; #define PG8_STAGE(bufoff, gbase, voff) do { _Pragma("unroll") for (int _i = 0; _i < 2; ++_i) \
;         __builtin_amdgcn_global_load_lds((const unsigned*)((const char*)(gbase) + (voff)[_i]), (PG8_LAS unsigned*)(lds + (bufoff) + ldsw + _i * 8192), 16, 0, 0); } while (0)
; #define PG8_LDA(dst, b, h) do { _Pragma("unroll") for (int m = 0; m < 4; ++m) _Pragma("unroll") for (int k = 0; k < 2; ++k) dst[m][k] = *(const PG8_LAS bf16x8*)(lds + PG8_SA(b, h) + aoff + m * 2048 + k * 1024); } while (0)
; #define PG8_LDB(dst, b, h) do { _Pragma("unroll") for (int n = 0; n < 2; ++n) _Pragma("unroll") for (int k = 0; k < 2; ++k) dst[n][k] = *(const PG8_LAS bf16x8*)(lds + PG8_SB(b, h) + boff + n * 2048 + k * 1024); } while (0)
; #define PG8_MMA(ai, bj, At, Bt) do { __builtin_amdgcn_s_setprio(1); _Pragma("unroll") for (int m = 0; m < 4; ++m) _Pragma("unroll") for (int n = 0; n < 2; ++n) _Pragma("unroll") for (int k = 0; k < 2; ++k) \
;         acc[ai][bj][m][n] = __builtin_amdgcn_mfma_f32_16x16x32_bf16(Bt[n][k], At[m][k], acc[ai][bj][m][n], 0, 0, 0); __builtin_amdgcn_s_setprio(0); } while (0)
; #define PG8_WAIT_V(n) asm volatile("s_waitcnt vmcnt(" #n ")" ::: "memory")
; #define PG8_WAIT_L(n) asm volatile("s_waitcnt lgkmcnt(" #n ")" ::: "memory")
; template <class Epi, class Sched, bool ALIGN_EPI = false, bool SP2 = false>
; __device__ __forceinline__ void gemm_phase(PG8_LAS unsigned char* lds, const Gemm g, const Sched& S, const Epi& E, const int tid) {
;     ...
;             const bool last = (t == nt - 2);
;             const char* a1 = cA + (size_t)(t + 1) * kstep;
;             const char* a2 = last ? nA : cA + (size_t)(t + 2) * kstep; const char* b2 = last ? nB : cB + (size_t)(t + 2) * kstep;
;             const char* a3 = a2 + kstep; const char* b3 = b2 + kstep;
;             if (last && has_next) S.a_ready(nxt);
;             if constexpr (SP2) {
;             PG8_LDB(B0, 0, 0); PG8_LDB(B1, 0, 1); PG8_SCHED; PG8_LDA(At, 0, 0); PG8_STAGE(PG8_SA(1, 1), a1 + hstep, voffA);
;             PG8_WAIT_V(8); PG8_WAIT_L(0); PG8_BAR; PG8_MMA(0, 0, At, B0); PG8_MMA(0, 1, At, B1); PG8_BAR; PG8_SCHED;
;             PG8_LDA(At, 0, 1); PG8_STAGE(PG8_SB(0, 0), b2, voffB); PG8_STAGE(PG8_SB(0, 1), b2 + hstep, voffB); PG8_STAGE(PG8_SA(0, 0), a2, voffA);
;             PG8_WAIT_V(8); PG8_WAIT_L(0); PG8_BAR; PG8_MMA(1, 0, At, B0); PG8_MMA(1, 1, At, B1); PG8_BAR; PG8_SCHED;
.LBB0_211:
	s_add_u32 s56, s54, 0xfff80080
	s_addc_u32 s57, s55, -1
	s_add_i32 s78, 0, 0x10000
	s_cmp_eq_u32 s77, 28
	s_cselect_b32 s59, s49, s57
	s_cselect_b32 s58, s72, s56
	s_cselect_b32 s57, s47, s76
	s_cselect_b32 s56, s73, s75
	s_add_i32 s80, 0, 0x14000
	v_add_u32_e32 v154, s78, v160
	v_add_u32_e32 v158, s80, v160
	ds_read_b128 v[142:145], v154
	ds_read_b128 v[146:149], v154 offset:1024
	ds_read_b128 v[150:153], v154 offset:2048
	ds_read_b128 v[154:157], v154 offset:3072
	ds_read_b128 v[164:167], v158
	ds_read_b128 v[168:171], v158 offset:1024
	ds_read_b128 v[172:175], v158 offset:2048
	ds_read_b128 v[176:179], v158 offset:3072
	v_lshl_add_u64 v[158:159], s[54:55], 0, v[140:141]
	s_add_i32 m0, s61, 0xc000
	ds_read_b128 v[186:189], v162
	ds_read_b128 v[190:193], v162 offset:1024
	ds_read_b128 v[194:197], v162 offset:2048
	ds_read_b128 v[198:201], v162 offset:3072
	ds_read_b128 v[202:205], v162 offset:4096
	ds_read_b128 v[206:209], v162 offset:5120
	ds_read_b128 v[210:213], v162 offset:6144
	ds_read_b128 v[214:217], v162 offset:7168
	global_load_lds_dwordx4 v[158:159], off
	v_lshl_add_u64 v[158:159], s[54:55], 0, v[138:139]
	s_add_i32 m0, s61, 0xe000
	s_nop 0
	global_load_lds_dwordx4 v[158:159], off
	s_waitcnt vmcnt(8)
	s_waitcnt lgkmcnt(0)
	s_setprio 1
	s_barrier
	v_mfma_f32_16x16x32_bf16 v[130:133], v[142:145], v[186:189], v[130:133]
	v_mfma_f32_16x16x32_bf16 v[126:129], v[150:153], v[186:189], v[126:129]
	v_mfma_f32_16x16x32_bf16 v[114:117], v[142:145], v[194:197], v[114:117]
	v_mfma_f32_16x16x32_bf16 v[106:109], v[150:153], v[194:197], v[106:109]
	v_mfma_f32_16x16x32_bf16 v[92:95], v[142:145], v[202:205], v[92:95]
	v_mfma_f32_16x16x32_bf16 v[84:87], v[150:153], v[202:205], v[84:87]
	v_mfma_f32_16x16x32_bf16 v[76:79], v[142:145], v[210:213], v[76:79]
	v_mfma_f32_16x16x32_bf16 v[68:71], v[150:153], v[210:213], v[68:71]
	v_mfma_f32_16x16x32_bf16 v[130:133], v[146:149], v[190:193], v[130:133]
	v_mfma_f32_16x16x32_bf16 v[126:129], v[154:157], v[190:193], v[126:129]
	v_mfma_f32_16x16x32_bf16 v[114:117], v[146:149], v[198:201], v[114:117]
	v_mfma_f32_16x16x32_bf16 v[106:109], v[154:157], v[198:201], v[106:109]
	v_mfma_f32_16x16x32_bf16 v[92:95], v[146:149], v[206:209], v[92:95]
	v_mfma_f32_16x16x32_bf16 v[84:87], v[154:157], v[206:209], v[84:87]
	v_mfma_f32_16x16x32_bf16 v[76:79], v[146:149], v[214:217], v[76:79]
	v_mfma_f32_16x16x32_bf16 v[68:71], v[154:157], v[214:217], v[68:71]
	v_mfma_f32_16x16x32_bf16 v[122:125], v[164:167], v[186:189], v[122:125]
	v_mfma_f32_16x16x32_bf16 v[118:121], v[172:175], v[186:189], v[118:121]
	v_mfma_f32_16x16x32_bf16 v[110:113], v[164:167], v[194:197], v[110:113]
	v_mfma_f32_16x16x32_bf16 v[102:105], v[172:175], v[194:197], v[102:105]
	v_mfma_f32_16x16x32_bf16 v[88:91], v[164:167], v[202:205], v[88:91]
	v_mfma_f32_16x16x32_bf16 v[80:83], v[172:175], v[202:205], v[80:83]
	v_mfma_f32_16x16x32_bf16 v[72:75], v[164:167], v[210:213], v[72:75]
	v_mfma_f32_16x16x32_bf16 v[64:67], v[172:175], v[210:213], v[64:67]
	v_mfma_f32_16x16x32_bf16 v[122:125], v[168:171], v[190:193], v[122:125]
	v_mfma_f32_16x16x32_bf16 v[118:121], v[176:179], v[190:193], v[118:121]
	v_mfma_f32_16x16x32_bf16 v[110:113], v[168:171], v[198:201], v[110:113]
	v_mfma_f32_16x16x32_bf16 v[102:105], v[176:179], v[198:201], v[102:105]
	v_mfma_f32_16x16x32_bf16 v[88:91], v[168:171], v[206:209], v[88:91]
	v_mfma_f32_16x16x32_bf16 v[80:83], v[176:179], v[206:209], v[80:83]
	v_mfma_f32_16x16x32_bf16 v[72:75], v[168:171], v[214:217], v[72:75]
	v_mfma_f32_16x16x32_bf16 v[64:67], v[176:179], v[214:217], v[64:67]
	s_barrier
	s_setprio 0
	s_add_i32 s78, s78, s60
	v_lshl_add_u64 v[158:159], s[56:57], 0, v[96:97]
	s_mov_b32 m0, s78
	ds_read_b128 v[186:189], v162 offset:16384
	ds_read_b128 v[190:193], v162 offset:17408
	ds_read_b128 v[194:197], v162 offset:18432
	ds_read_b128 v[198:201], v162 offset:19456
	ds_read_b128 v[202:205], v162 offset:20480
	ds_read_b128 v[206:209], v162 offset:21504
	ds_read_b128 v[210:213], v162 offset:22528
	ds_read_b128 v[214:217], v162 offset:23552
	global_load_lds_dwordx4 v[158:159], off
	s_add_i32 m0, s78, 0x2000
	s_add_u32 s78, s56, 0x80000
	v_lshl_add_u64 v[180:181], s[56:57], 0, v[98:99]
	s_addc_u32 s79, s57, 0
	s_add_i32 s80, s80, s60
	global_load_lds_dwordx4 v[180:181], off
	v_lshl_add_u64 v[218:219], s[78:79], 0, v[96:97]
	s_mov_b32 m0, s80
	v_lshl_add_u64 v[220:221], s[58:59], 0, v[134:135]
	global_load_lds_dwordx4 v[218:219], off
	v_lshl_add_u64 v[218:219], s[78:79], 0, v[98:99]
	s_add_i32 m0, s80, 0x2000
	s_nop 0
	global_load_lds_dwordx4 v[218:219], off
	v_lshl_add_u64 v[218:219], s[58:59], 0, v[136:137]
	s_mov_b32 m0, s61
	s_nop 0
	global_load_lds_dwordx4 v[218:219], off
	s_mov_b32 m0, s64
	s_nop 0
	global_load_lds_dwordx4 v[220:221], off
	s_waitcnt vmcnt(8)
	s_waitcnt lgkmcnt(0)
	s_setprio 1
	s_barrier
; #define PG8_STAGE(bufoff, gbase, voff) do { _Pragma("unroll") for (int _i = 0; _i < 2; ++_i) \
;         __builtin_amdgcn_global_load_lds((const unsigned*)((const char*)(gbase) + (voff)[_i]), (PG8_LAS unsigned*)(lds + (bufoff) + ldsw + _i * 8192), 16, 0, 0); } while (0)
; #define PG8_LDA(dst, b, h) do { _Pragma("unroll") for (int m = 0; m < 4; ++m) _Pragma("unroll") for (int k = 0; k < 2; ++k) dst[m][k] = *(const PG8_LAS bf16x8*)(lds + PG8_SA(b, h) + aoff + m * 2048 + k * 1024); } while (0)
; #define PG8_LDB(dst, b, h) do { _Pragma("unroll") for (int n = 0; n < 2; ++n) _Pragma("unroll") for (int k = 0; k < 2; ++k) dst[n][k] = *(const PG8_LAS bf16x8*)(lds + PG8_SB(b, h) + boff + n * 2048 + k * 1024); } while (0)
; #define PG8_MMA(ai, bj, At, Bt) do { __builtin_amdgcn_s_setprio(1); _Pragma("unroll") for (int m = 0; m < 4; ++m) _Pragma("unroll") for (int n = 0; n < 2; ++n) _Pragma("unroll") for (int k = 0; k < 2; ++k) \
;         acc[ai][bj][m][n] = __builtin_amdgcn_mfma_f32_16x16x32_bf16(Bt[n][k], At[m][k], acc[ai][bj][m][n], 0, 0, 0); __builtin_amdgcn_s_setprio(0); } while (0)
; #define PG8_WAIT_V(n) asm volatile("s_waitcnt vmcnt(" #n ")" ::: "memory")
; #define PG8_WAIT_L(n) asm volatile("s_waitcnt lgkmcnt(" #n ")" ::: "memory")
; #define PG8_BAR __builtin_amdgcn_s_barrier()
; #define PG8_SCHED __builtin_amdgcn_sched_barrier(0)
; template <class Epi, class Sched, bool ALIGN_EPI = false, bool SP2 = false>
; __device__ __forceinline__ void gemm_phase(PG8_LAS unsigned char* lds, const Gemm g, const Sched& S, const Epi& E, const int tid) {
;     ...
;             PG8_WAIT_V(8); PG8_WAIT_L(0); PG8_BAR; PG8_MMA(0, 0, At, B0); PG8_MMA(0, 1, At, B1); PG8_BAR; PG8_SCHED;
;             PG8_LDA(At, 0, 1); PG8_STAGE(PG8_SB(0, 0), b2, voffB); PG8_STAGE(PG8_SB(0, 1), b2 + hstep, voffB); PG8_STAGE(PG8_SA(0, 0), a2, voffA);
;             PG8_WAIT_V(8); PG8_WAIT_L(0); PG8_BAR; PG8_MMA(1, 0, At, B0); PG8_MMA(1, 1, At, B1); PG8_BAR; PG8_SCHED;
;             PG8_LDB(B0, 1, 0); PG8_LDB(B1, 1, 1); PG8_SCHED; PG8_LDA(At, 1, 0); PG8_STAGE(PG8_SA(0, 1), a2 + hstep, voffA);
;             PG8_WAIT_V(8); PG8_WAIT_L(0); PG8_BAR; PG8_MMA(0, 0, At, B0); PG8_MMA(0, 1, At, B1); PG8_BAR; PG8_SCHED;
	v_mfma_f32_16x16x32_bf16 v[60:63], v[142:145], v[186:189], v[60:63]
	v_mfma_f32_16x16x32_bf16 v[52:55], v[150:153], v[186:189], v[52:55]
	v_mfma_f32_16x16x32_bf16 v[44:47], v[142:145], v[194:197], v[44:47]
	v_mfma_f32_16x16x32_bf16 v[36:39], v[150:153], v[194:197], v[36:39]
	v_mfma_f32_16x16x32_bf16 v[28:31], v[142:145], v[202:205], v[28:31]
	v_mfma_f32_16x16x32_bf16 v[20:23], v[150:153], v[202:205], v[20:23]
	v_mfma_f32_16x16x32_bf16 v[12:15], v[142:145], v[210:213], v[12:15]
	v_mfma_f32_16x16x32_bf16 v[4:7], v[150:153], v[210:213], v[4:7]
	v_mfma_f32_16x16x32_bf16 v[60:63], v[146:149], v[190:193], v[60:63]
	v_mfma_f32_16x16x32_bf16 v[52:55], v[154:157], v[190:193], v[52:55]
	v_mfma_f32_16x16x32_bf16 v[44:47], v[146:149], v[198:201], v[44:47]
	v_mfma_f32_16x16x32_bf16 v[36:39], v[154:157], v[198:201], v[36:39]
	v_mfma_f32_16x16x32_bf16 v[28:31], v[146:149], v[206:209], v[28:31]
	v_mfma_f32_16x16x32_bf16 v[20:23], v[154:157], v[206:209], v[20:23]
	v_mfma_f32_16x16x32_bf16 v[12:15], v[146:149], v[214:217], v[12:15]
	v_mfma_f32_16x16x32_bf16 v[4:7], v[154:157], v[214:217], v[4:7]
	v_mfma_f32_16x16x32_bf16 v[56:59], v[164:167], v[186:189], v[56:59]
	v_mfma_f32_16x16x32_bf16 v[48:51], v[172:175], v[186:189], v[48:51]
	v_mfma_f32_16x16x32_bf16 v[40:43], v[164:167], v[194:197], v[40:43]
	v_mfma_f32_16x16x32_bf16 v[32:35], v[172:175], v[194:197], v[32:35]
	v_mfma_f32_16x16x32_bf16 v[24:27], v[164:167], v[202:205], v[24:27]
	v_mfma_f32_16x16x32_bf16 v[16:19], v[172:175], v[202:205], v[16:19]
	v_mfma_f32_16x16x32_bf16 v[8:11], v[164:167], v[210:213], v[8:11]
	v_mfma_f32_16x16x32_bf16 v[0:3], v[172:175], v[210:213], v[0:3]
	v_mfma_f32_16x16x32_bf16 v[56:59], v[168:171], v[190:193], v[56:59]
	v_mfma_f32_16x16x32_bf16 v[48:51], v[176:179], v[190:193], v[48:51]
	v_mfma_f32_16x16x32_bf16 v[40:43], v[168:171], v[198:201], v[40:43]
	v_mfma_f32_16x16x32_bf16 v[32:35], v[176:179], v[198:201], v[32:35]
	v_mfma_f32_16x16x32_bf16 v[24:27], v[168:171], v[206:209], v[24:27]
	v_mfma_f32_16x16x32_bf16 v[16:19], v[176:179], v[206:209], v[16:19]
	v_mfma_f32_16x16x32_bf16 v[8:11], v[168:171], v[214:217], v[8:11]
	v_mfma_f32_16x16x32_bf16 v[0:3], v[176:179], v[214:217], v[0:3]
	s_barrier
	s_setprio 0
	s_add_i32 s78, 0, 0x18000
	s_add_i32 s79, 0, 0x1c000
	v_add_u32_e32 v154, s78, v160
	v_add_u32_e32 v163, s79, v160
	ds_read_b128 v[142:145], v154
	ds_read_b128 v[146:149], v154 offset:1024
	ds_read_b128 v[150:153], v154 offset:2048
	ds_read_b128 v[154:157], v154 offset:3072
	ds_read_b128 v[164:167], v163
	ds_read_b128 v[168:171], v163 offset:1024
	ds_read_b128 v[172:175], v163 offset:2048
	ds_read_b128 v[176:179], v163 offset:3072
	s_add_u32 s58, s58, 0x80000
	s_addc_u32 s59, s59, 0
	s_mov_b32 m0, s65
	v_lshl_add_u64 v[222:223], s[58:59], 0, v[136:137]
	ds_read_b128 v[186:189], v162 offset:32768
	ds_read_b128 v[190:193], v162 offset:33792
	ds_read_b128 v[194:197], v162 offset:34816
	ds_read_b128 v[198:201], v162 offset:35840
	ds_read_b128 v[202:205], v162 offset:36864
	ds_read_b128 v[206:209], v162 offset:37888
	ds_read_b128 v[210:213], v162 offset:38912
	ds_read_b128 v[214:217], v162 offset:39936
	global_load_lds_dwordx4 v[222:223], off
	v_lshl_add_u64 v[222:223], s[58:59], 0, v[134:135]
	s_mov_b32 m0, s66
	s_nop 0
	global_load_lds_dwordx4 v[222:223], off
	s_waitcnt vmcnt(8)
	s_waitcnt lgkmcnt(0)
	s_setprio 1
	s_barrier
	v_mfma_f32_16x16x32_bf16 v[130:133], v[142:145], v[186:189], v[130:133]
	v_mfma_f32_16x16x32_bf16 v[126:129], v[150:153], v[186:189], v[126:129]
	v_mfma_f32_16x16x32_bf16 v[114:117], v[142:145], v[194:197], v[114:117]
	v_mfma_f32_16x16x32_bf16 v[106:109], v[150:153], v[194:197], v[106:109]
	v_mfma_f32_16x16x32_bf16 v[92:95], v[142:145], v[202:205], v[92:95]
	v_mfma_f32_16x16x32_bf16 v[84:87], v[150:153], v[202:205], v[84:87]
	v_mfma_f32_16x16x32_bf16 v[76:79], v[142:145], v[210:213], v[76:79]
	v_mfma_f32_16x16x32_bf16 v[68:71], v[150:153], v[210:213], v[68:71]
	v_mfma_f32_16x16x32_bf16 v[130:133], v[146:149], v[190:193], v[130:133]
	v_mfma_f32_16x16x32_bf16 v[126:129], v[154:157], v[190:193], v[126:129]
	v_mfma_f32_16x16x32_bf16 v[114:117], v[146:149], v[198:201], v[114:117]
	v_mfma_f32_16x16x32_bf16 v[106:109], v[154:157], v[198:201], v[106:109]
	v_mfma_f32_16x16x32_bf16 v[92:95], v[146:149], v[206:209], v[92:95]
	v_mfma_f32_16x16x32_bf16 v[84:87], v[154:157], v[206:209], v[84:87]
	v_mfma_f32_16x16x32_bf16 v[76:79], v[146:149], v[214:217], v[76:79]
	v_mfma_f32_16x16x32_bf16 v[68:71], v[154:157], v[214:217], v[68:71]
	v_mfma_f32_16x16x32_bf16 v[122:125], v[164:167], v[186:189], v[122:125]
	v_mfma_f32_16x16x32_bf16 v[118:121], v[172:175], v[186:189], v[118:121]
	v_mfma_f32_16x16x32_bf16 v[110:113], v[164:167], v[194:197], v[110:113]
	v_mfma_f32_16x16x32_bf16 v[102:105], v[172:175], v[194:197], v[102:105]
	v_mfma_f32_16x16x32_bf16 v[88:91], v[164:167], v[202:205], v[88:91]
	v_mfma_f32_16x16x32_bf16 v[80:83], v[172:175], v[202:205], v[80:83]
	v_mfma_f32_16x16x32_bf16 v[72:75], v[164:167], v[210:213], v[72:75]
	v_mfma_f32_16x16x32_bf16 v[64:67], v[172:175], v[210:213], v[64:67]
	v_mfma_f32_16x16x32_bf16 v[122:125], v[168:171], v[190:193], v[122:125]
	v_mfma_f32_16x16x32_bf16 v[118:121], v[176:179], v[190:193], v[118:121]
	v_mfma_f32_16x16x32_bf16 v[110:113], v[168:171], v[198:201], v[110:113]
	v_mfma_f32_16x16x32_bf16 v[102:105], v[176:179], v[198:201], v[102:105]
	v_mfma_f32_16x16x32_bf16 v[88:91], v[168:171], v[206:209], v[88:91]
	v_mfma_f32_16x16x32_bf16 v[80:83], v[176:179], v[206:209], v[80:83]
	v_mfma_f32_16x16x32_bf16 v[72:75], v[168:171], v[214:217], v[72:75]
	v_mfma_f32_16x16x32_bf16 v[64:67], v[176:179], v[214:217], v[64:67]
	s_barrier
; #define PG8_STAGE(bufoff, gbase, voff) do { _Pragma("unroll") for (int _i = 0; _i < 2; ++_i) \
;         __builtin_amdgcn_global_load_lds((const unsigned*)((const char*)(gbase) + (voff)[_i]), (PG8_LAS unsigned*)(lds + (bufoff) + ldsw + _i * 8192), 16, 0, 0); } while (0)
; #define PG8_WAIT_V(n) asm volatile("s_waitcnt vmcnt(" #n ")" ::: "memory")
; #define PG8_WAIT_L(n) asm volatile("s_waitcnt lgkmcnt(" #n ")" ::: "memory")
; template <class Epi, class Sched, bool ALIGN_EPI = false, bool SP2 = false>
; __device__ __forceinline__ void gemm_phase(PG8_LAS unsigned char* lds, const Gemm g, const Sched& S, const Epi& E, const int tid) {
;     ...
;             PG8_WAIT_V(8); PG8_WAIT_L(0); PG8_BAR; PG8_MMA(0, 0, At, B0); PG8_MMA(0, 1, At, B1); PG8_BAR; PG8_SCHED;
;             PG8_LDA(At, 1, 1); PG8_STAGE(PG8_SB(1, 0), b3, voffB); PG8_STAGE(PG8_SB(1, 1), b3 + hstep, voffB); PG8_STAGE(PG8_SA(1, 0), a3, voffA);
;             PG8_WAIT_V(8); PG8_WAIT_L(0); PG8_BAR; PG8_MMA(1, 0, At, B0); PG8_MMA(1, 1, At, B1); PG8_BAR; PG8_SCHED;
;             } else {
;             PG8_LDB(B0, 0, 0); PG8_SCHED; PG8_LDA(At, 0, 0); PG8_STAGE(PG8_SA(1, 1), a1 + hstep, voffA);
;             PG8_WAIT_L(8); PG8_BAR; PG8_WAIT_L(0); PG8_MMA(0, 0, At, B0); PG8_BAR; PG8_SCHED;
;             PG8_LDB(B1, 0, 1); PG8_STAGE(PG8_SB(0, 0), b2, voffB);
;             PG8_BAR; PG8_WAIT_L(0); PG8_MMA(0, 1, At, B1); PG8_BAR;
;             PG8_LDA(At, 0, 1); PG8_STAGE(PG8_SA(0, 0), a2, voffA);
;             PG8_BAR; PG8_WAIT_L(0); PG8_MMA(1, 0, At, B0); PG8_BAR; PG8_SCHED;
;             PG8_STAGE(PG8_SB(0, 1), b2 + hstep, voffB);
;             PG8_WAIT_V(6); PG8_BAR; PG8_MMA(1, 1, At, B1); PG8_BAR;
;             PG8_LDB(B0, 1, 0); PG8_SCHED; PG8_LDA(At, 1, 0); PG8_STAGE(PG8_SA(0, 1), a2 + hstep, voffA);
;             PG8_WAIT_L(8); PG8_BAR; PG8_WAIT_L(0); PG8_MMA(0, 0, At, B0); PG8_BAR; PG8_SCHED;
;             PG8_LDB(B1, 1, 1); PG8_STAGE(PG8_SB(1, 0), b3, voffB);
;             PG8_BAR; PG8_WAIT_L(0); PG8_MMA(0, 1, At, B1); PG8_BAR;
;             PG8_LDA(At, 1, 1); PG8_STAGE(PG8_SA(1, 0), a3, voffA);
;             PG8_BAR; PG8_WAIT_L(0); PG8_MMA(1, 0, At, B0); PG8_BAR; PG8_SCHED;
;             PG8_STAGE(PG8_SB(1, 1), b3 + hstep, voffB);
;             PG8_WAIT_V(6); PG8_BAR; PG8_MMA(1, 1, At, B1); PG8_BAR;
;             }
;         }
;         if constexpr (ALIGN_EPI) { if (wr == 0) PG8_BAR; }
	s_setprio 0
	s_add_i32 s58, s78, s60
	v_lshl_add_u64 v[158:159], v[158:159], 0, s[28:29]
	s_mov_b32 m0, s58
	ds_read_b128 v[186:189], v162 offset:49152
	ds_read_b128 v[190:193], v162 offset:50176
	ds_read_b128 v[194:197], v162 offset:51200
	ds_read_b128 v[198:201], v162 offset:52224
	ds_read_b128 v[202:205], v162 offset:53248
	ds_read_b128 v[206:209], v162 offset:54272
	ds_read_b128 v[210:213], v162 offset:55296
	ds_read_b128 v[214:217], v162 offset:56320
	global_load_lds_dwordx4 v[158:159], off
	s_add_i32 m0, s58, 0x2000
	s_add_u32 s56, s56, 0x80080
	v_lshl_add_u64 v[158:159], v[180:181], 0, s[28:29]
	s_addc_u32 s57, s57, 0
	s_add_i32 s58, s79, s60
	global_load_lds_dwordx4 v[158:159], off
	v_lshl_add_u64 v[158:159], s[56:57], 0, v[96:97]
	s_mov_b32 m0, s58
	s_nop 0
	global_load_lds_dwordx4 v[158:159], off
	v_lshl_add_u64 v[158:159], s[56:57], 0, v[98:99]
	s_add_i32 m0, s58, 0x2000
	s_nop 0
	global_load_lds_dwordx4 v[158:159], off
	v_lshl_add_u64 v[158:159], v[218:219], 0, s[28:29]
	s_mov_b32 m0, s67
	s_nop 0
	global_load_lds_dwordx4 v[158:159], off
	v_lshl_add_u64 v[158:159], v[220:221], 0, s[28:29]
	s_mov_b32 m0, s68
	s_nop 0
	global_load_lds_dwordx4 v[158:159], off
	s_waitcnt vmcnt(8)
	s_waitcnt lgkmcnt(0)
	s_setprio 1
	s_barrier
	v_mfma_f32_16x16x32_bf16 v[60:63], v[142:145], v[186:189], v[60:63]
	v_mfma_f32_16x16x32_bf16 v[52:55], v[150:153], v[186:189], v[52:55]
	v_mfma_f32_16x16x32_bf16 v[44:47], v[142:145], v[194:197], v[44:47]
	v_mfma_f32_16x16x32_bf16 v[36:39], v[150:153], v[194:197], v[36:39]
	v_mfma_f32_16x16x32_bf16 v[28:31], v[142:145], v[202:205], v[28:31]
	v_mfma_f32_16x16x32_bf16 v[20:23], v[150:153], v[202:205], v[20:23]
	v_mfma_f32_16x16x32_bf16 v[12:15], v[142:145], v[210:213], v[12:15]
	v_mfma_f32_16x16x32_bf16 v[4:7], v[150:153], v[210:213], v[4:7]
	v_mfma_f32_16x16x32_bf16 v[60:63], v[146:149], v[190:193], v[60:63]
	v_mfma_f32_16x16x32_bf16 v[52:55], v[154:157], v[190:193], v[52:55]
	v_mfma_f32_16x16x32_bf16 v[44:47], v[146:149], v[198:201], v[44:47]
	v_mfma_f32_16x16x32_bf16 v[36:39], v[154:157], v[198:201], v[36:39]
	v_mfma_f32_16x16x32_bf16 v[28:31], v[146:149], v[206:209], v[28:31]
	v_mfma_f32_16x16x32_bf16 v[20:23], v[154:157], v[206:209], v[20:23]
	v_mfma_f32_16x16x32_bf16 v[12:15], v[146:149], v[214:217], v[12:15]
	v_mfma_f32_16x16x32_bf16 v[4:7], v[154:157], v[214:217], v[4:7]
	v_mfma_f32_16x16x32_bf16 v[56:59], v[164:167], v[186:189], v[56:59]
	v_mfma_f32_16x16x32_bf16 v[48:51], v[172:175], v[186:189], v[48:51]
	v_mfma_f32_16x16x32_bf16 v[40:43], v[164:167], v[194:197], v[40:43]
	v_mfma_f32_16x16x32_bf16 v[32:35], v[172:175], v[194:197], v[32:35]
	v_mfma_f32_16x16x32_bf16 v[24:27], v[164:167], v[202:205], v[24:27]
	v_mfma_f32_16x16x32_bf16 v[16:19], v[172:175], v[202:205], v[16:19]
	v_mfma_f32_16x16x32_bf16 v[8:11], v[164:167], v[210:213], v[8:11]
	v_mfma_f32_16x16x32_bf16 v[0:3], v[172:175], v[210:213], v[0:3]
	v_mfma_f32_16x16x32_bf16 v[56:59], v[168:171], v[190:193], v[56:59]
	v_mfma_f32_16x16x32_bf16 v[48:51], v[176:179], v[190:193], v[48:51]
	v_mfma_f32_16x16x32_bf16 v[40:43], v[168:171], v[198:201], v[40:43]
	v_mfma_f32_16x16x32_bf16 v[32:35], v[176:179], v[198:201], v[32:35]
	v_mfma_f32_16x16x32_bf16 v[24:27], v[168:171], v[206:209], v[24:27]
	v_mfma_f32_16x16x32_bf16 v[16:19], v[176:179], v[206:209], v[16:19]
	v_mfma_f32_16x16x32_bf16 v[8:11], v[168:171], v[214:217], v[8:11]
	v_mfma_f32_16x16x32_bf16 v[0:3], v[176:179], v[214:217], v[0:3]
	s_barrier
	s_setprio 0
	s_add_i32 s77, s77, 2
	s_add_u32 s75, s75, 0x100
	s_addc_u32 s76, s76, 0
	s_add_u32 s54, s54, 0x100
	s_addc_u32 s55, s55, 0
	s_cmp_gt_u32 s77, 29
	s_cbranch_scc0 .LBB0_211
	s_and_b64 vcc, exec, s[44:45]
	s_cbranch_vccz .LBB0_214
	s_barrier

; #define PG8_STAGE(bufoff, gbase, voff) do { _Pragma("unroll") for (int _i = 0; _i < 2; ++_i) \
;         __builtin_amdgcn_global_load_lds((const unsigned*)((const char*)(gbase) + (voff)[_i]), (PG8_LAS unsigned*)(lds + (bufoff) + ldsw + _i * 8192), 16, 0, 0); } while (0)
; #define PG8_LDA(dst, b, h) do { _Pragma("unroll") for (int m = 0; m < 4; ++m) _Pragma("unroll") for (int k = 0; k < 2; ++k) dst[m][k] = *(const PG8_LAS bf16x8*)(lds + PG8_SA(b, h) + aoff + m * 2048 + k * 1024); } while (0)
; #define PG8_LDB(dst, b, h) do { _Pragma("unroll") for (int n = 0; n < 2; ++n) _Pragma("unroll") for (int k = 0; k < 2; ++k) dst[n][k] = *(const PG8_LAS bf16x8*)(lds + PG8_SB(b, h) + boff + n * 2048 + k * 1024); } while (0)
; #define PG8_MMA(ai, bj, At, Bt) do { __builtin_amdgcn_s_setprio(1); _Pragma("unroll") for (int m = 0; m < 4; ++m) _Pragma("unroll") for (int n = 0; n < 2; ++n) _Pragma("unroll") for (int k = 0; k < 2; ++k) \
;         acc[ai][bj][m][n] = __builtin_amdgcn_mfma_f32_16x16x32_bf16(Bt[n][k], At[m][k], acc[ai][bj][m][n], 0, 0, 0); __builtin_amdgcn_s_setprio(0); } while (0)
; #define PG8_WAIT_V(n) asm volatile("s_waitcnt vmcnt(" #n ")" ::: "memory")
; #define PG8_WAIT_L(n) asm volatile("s_waitcnt lgkmcnt(" #n ")" ::: "memory")
; template <class Epi, class Sched, bool ALIGN_EPI = false, bool SP2 = false>
; __device__ __forceinline__ void gemm_phase(PG8_LAS unsigned char* lds, const Gemm g, const Sched& S, const Epi& E, const int tid) {
;     ...
;             const bool last = (t == nt - 2);
;             const char* a1 = cA + (size_t)(t + 1) * kstep;
;             const char* a2 = last ? nA : cA + (size_t)(t + 2) * kstep; const char* b2 = last ? nB : cB + (size_t)(t + 2) * kstep;
;             const char* a3 = a2 + kstep; const char* b3 = b2 + kstep;
;             if (last && has_next) S.a_ready(nxt);
;             if constexpr (SP2) {
;             PG8_LDB(B0, 0, 0); PG8_LDB(B1, 0, 1); PG8_SCHED; PG8_LDA(At, 0, 0); PG8_STAGE(PG8_SA(1, 1), a1 + hstep, voffA);
;             PG8_WAIT_V(8); PG8_WAIT_L(0); PG8_BAR; PG8_MMA(0, 0, At, B0); PG8_MMA(0, 1, At, B1); PG8_BAR; PG8_SCHED;
;             PG8_LDA(At, 0, 1); PG8_STAGE(PG8_SB(0, 0), b2, voffB); PG8_STAGE(PG8_SB(0, 1), b2 + hstep, voffB); PG8_STAGE(PG8_SA(0, 0), a2, voffA);
;             PG8_WAIT_V(8); PG8_WAIT_L(0); PG8_BAR; PG8_MMA(1, 0, At, B0); PG8_MMA(1, 1, At, B1); PG8_BAR; PG8_SCHED;
.LBB0_403:
	s_add_u32 s52, s50, 0x100
	s_addc_u32 s53, s51, 0
	s_add_i32 s76, 0, 0x10000
	s_cmpk_eq_i32 s75, 0x54
	s_cselect_b32 s57, s45, s53
	s_cselect_b32 s56, s44, s52
	s_cselect_b32 s55, s47, s73
	s_cselect_b32 s54, s46, s72
	s_add_i32 s77, 0, 0x14000
	v_add_u32_e32 v146, s76, v233
	v_add_u32_e32 v162, s77, v233
	ds_read_b128 v[126:129], v146
	ds_read_b128 v[130:133], v146 offset:1024
	ds_read_b128 v[142:145], v146 offset:2048
	ds_read_b128 v[146:149], v146 offset:3072
	ds_read_b128 v[150:153], v162
	ds_read_b128 v[154:157], v162 offset:1024
	ds_read_b128 v[158:161], v162 offset:2048
	ds_read_b128 v[162:165], v162 offset:3072
	v_lshl_add_u64 v[210:211], s[50:51], 0, v[192:193]
	s_add_i32 m0, s60, 0xc000
	ds_read_b128 v[166:169], v236
	ds_read_b128 v[170:173], v236 offset:1024
	ds_read_b128 v[174:177], v236 offset:2048
	ds_read_b128 v[178:181], v236 offset:3072
	ds_read_b128 v[194:197], v236 offset:4096
	ds_read_b128 v[198:201], v236 offset:5120
	ds_read_b128 v[202:205], v236 offset:6144
	ds_read_b128 v[206:209], v236 offset:7168
	global_load_lds_dwordx4 v[210:211], off
	v_lshl_add_u64 v[210:211], s[50:51], 0, v[190:191]
	s_add_i32 m0, s60, 0xe000
	s_nop 0
	global_load_lds_dwordx4 v[210:211], off
	s_waitcnt vmcnt(8)
	s_waitcnt lgkmcnt(0)
	s_setprio 1
	s_barrier
	v_mfma_f32_16x16x32_bf16 v[138:141], v[126:129], v[166:169], v[138:141]
	v_mfma_f32_16x16x32_bf16 v[134:137], v[142:145], v[166:169], v[134:137]
	v_mfma_f32_16x16x32_bf16 v[114:117], v[126:129], v[174:177], v[114:117]
	v_mfma_f32_16x16x32_bf16 v[110:113], v[142:145], v[174:177], v[110:113]
	v_mfma_f32_16x16x32_bf16 v[92:95], v[126:129], v[194:197], v[92:95]
	v_mfma_f32_16x16x32_bf16 v[88:91], v[142:145], v[194:197], v[88:91]
	v_mfma_f32_16x16x32_bf16 v[76:79], v[126:129], v[202:205], v[76:79]
	v_mfma_f32_16x16x32_bf16 v[72:75], v[142:145], v[202:205], v[72:75]
	v_mfma_f32_16x16x32_bf16 v[138:141], v[130:133], v[170:173], v[138:141]
	v_mfma_f32_16x16x32_bf16 v[134:137], v[146:149], v[170:173], v[134:137]
	v_mfma_f32_16x16x32_bf16 v[114:117], v[130:133], v[178:181], v[114:117]
	v_mfma_f32_16x16x32_bf16 v[110:113], v[146:149], v[178:181], v[110:113]
	v_mfma_f32_16x16x32_bf16 v[92:95], v[130:133], v[198:201], v[92:95]
	v_mfma_f32_16x16x32_bf16 v[88:91], v[146:149], v[198:201], v[88:91]
	v_mfma_f32_16x16x32_bf16 v[76:79], v[130:133], v[206:209], v[76:79]
	v_mfma_f32_16x16x32_bf16 v[72:75], v[146:149], v[206:209], v[72:75]
	v_mfma_f32_16x16x32_bf16 v[122:125], v[150:153], v[166:169], v[122:125]
	v_mfma_f32_16x16x32_bf16 v[118:121], v[158:161], v[166:169], v[118:121]
	v_mfma_f32_16x16x32_bf16 v[106:109], v[150:153], v[174:177], v[106:109]
	v_mfma_f32_16x16x32_bf16 v[102:105], v[158:161], v[174:177], v[102:105]
	v_mfma_f32_16x16x32_bf16 v[84:87], v[150:153], v[194:197], v[84:87]
	v_mfma_f32_16x16x32_bf16 v[80:83], v[158:161], v[194:197], v[80:83]
	v_mfma_f32_16x16x32_bf16 v[68:71], v[150:153], v[202:205], v[68:71]
	v_mfma_f32_16x16x32_bf16 v[64:67], v[158:161], v[202:205], v[64:67]
	v_mfma_f32_16x16x32_bf16 v[122:125], v[154:157], v[170:173], v[122:125]
	v_mfma_f32_16x16x32_bf16 v[118:121], v[162:165], v[170:173], v[118:121]
	v_mfma_f32_16x16x32_bf16 v[106:109], v[154:157], v[178:181], v[106:109]
	v_mfma_f32_16x16x32_bf16 v[102:105], v[162:165], v[178:181], v[102:105]
	v_mfma_f32_16x16x32_bf16 v[84:87], v[154:157], v[198:201], v[84:87]
	v_mfma_f32_16x16x32_bf16 v[80:83], v[162:165], v[198:201], v[80:83]
	v_mfma_f32_16x16x32_bf16 v[68:71], v[154:157], v[206:209], v[68:71]
	v_mfma_f32_16x16x32_bf16 v[64:67], v[162:165], v[206:209], v[64:67]
	s_barrier
	s_setprio 0
	s_add_i32 s50, s76, s59
	v_lshl_add_u64 v[210:211], s[54:55], 0, v[96:97]
	s_mov_b32 m0, s50
	ds_read_b128 v[166:169], v236 offset:16384
	ds_read_b128 v[170:173], v236 offset:17408
	ds_read_b128 v[174:177], v236 offset:18432
	ds_read_b128 v[178:181], v236 offset:19456
	ds_read_b128 v[194:197], v236 offset:20480
	ds_read_b128 v[198:201], v236 offset:21504
	ds_read_b128 v[202:205], v236 offset:22528
	ds_read_b128 v[206:209], v236 offset:23552
	global_load_lds_dwordx4 v[210:211], off
	s_add_i32 m0, s50, 0x2000
	s_add_u32 s50, s54, 0x160000
	v_lshl_add_u64 v[212:213], s[54:55], 0, v[98:99]
	s_addc_u32 s51, s55, 0
	s_add_i32 s76, s77, s59
	global_load_lds_dwordx4 v[212:213], off
	v_lshl_add_u64 v[214:215], s[50:51], 0, v[96:97]
	s_mov_b32 m0, s76
	v_lshl_add_u64 v[216:217], s[56:57], 0, v[186:187]
	global_load_lds_dwordx4 v[214:215], off
	v_lshl_add_u64 v[214:215], s[50:51], 0, v[98:99]
	s_add_i32 m0, s76, 0x2000
	s_nop 0
	global_load_lds_dwordx4 v[214:215], off
	v_lshl_add_u64 v[214:215], s[56:57], 0, v[188:189]
	s_mov_b32 m0, s60
	s_nop 0
	global_load_lds_dwordx4 v[214:215], off
	s_mov_b32 m0, s61
	s_nop 0
	global_load_lds_dwordx4 v[216:217], off
	s_waitcnt vmcnt(8)
	s_waitcnt lgkmcnt(0)
	s_setprio 1
	s_barrier
; #define PG8_STAGE(bufoff, gbase, voff) do { _Pragma("unroll") for (int _i = 0; _i < 2; ++_i) \
;         __builtin_amdgcn_global_load_lds((const unsigned*)((const char*)(gbase) + (voff)[_i]), (PG8_LAS unsigned*)(lds + (bufoff) + ldsw + _i * 8192), 16, 0, 0); } while (0)
; #define PG8_LDA(dst, b, h) do { _Pragma("unroll") for (int m = 0; m < 4; ++m) _Pragma("unroll") for (int k = 0; k < 2; ++k) dst[m][k] = *(const PG8_LAS bf16x8*)(lds + PG8_SA(b, h) + aoff + m * 2048 + k * 1024); } while (0)
; #define PG8_LDB(dst, b, h) do { _Pragma("unroll") for (int n = 0; n < 2; ++n) _Pragma("unroll") for (int k = 0; k < 2; ++k) dst[n][k] = *(const PG8_LAS bf16x8*)(lds + PG8_SB(b, h) + boff + n * 2048 + k * 1024); } while (0)
; #define PG8_MMA(ai, bj, At, Bt) do { __builtin_amdgcn_s_setprio(1); _Pragma("unroll") for (int m = 0; m < 4; ++m) _Pragma("unroll") for (int n = 0; n < 2; ++n) _Pragma("unroll") for (int k = 0; k < 2; ++k) \
;         acc[ai][bj][m][n] = __builtin_amdgcn_mfma_f32_16x16x32_bf16(Bt[n][k], At[m][k], acc[ai][bj][m][n], 0, 0, 0); __builtin_amdgcn_s_setprio(0); } while (0)
; #define PG8_WAIT_V(n) asm volatile("s_waitcnt vmcnt(" #n ")" ::: "memory")
; #define PG8_WAIT_L(n) asm volatile("s_waitcnt lgkmcnt(" #n ")" ::: "memory")
; #define PG8_BAR __builtin_amdgcn_s_barrier()
; #define PG8_SCHED __builtin_amdgcn_sched_barrier(0)
; template <class Epi, class Sched, bool ALIGN_EPI = false, bool SP2 = false>
; __device__ __forceinline__ void gemm_phase(PG8_LAS unsigned char* lds, const Gemm g, const Sched& S, const Epi& E, const int tid) {
;     ...
;             PG8_WAIT_V(8); PG8_WAIT_L(0); PG8_BAR; PG8_MMA(0, 0, At, B0); PG8_MMA(0, 1, At, B1); PG8_BAR; PG8_SCHED;
;             PG8_LDA(At, 0, 1); PG8_STAGE(PG8_SB(0, 0), b2, voffB); PG8_STAGE(PG8_SB(0, 1), b2 + hstep, voffB); PG8_STAGE(PG8_SA(0, 0), a2, voffA);
;             PG8_WAIT_V(8); PG8_WAIT_L(0); PG8_BAR; PG8_MMA(1, 0, At, B0); PG8_MMA(1, 1, At, B1); PG8_BAR; PG8_SCHED;
;             PG8_LDB(B0, 1, 0); PG8_LDB(B1, 1, 1); PG8_SCHED; PG8_LDA(At, 1, 0); PG8_STAGE(PG8_SA(0, 1), a2 + hstep, voffA);
;             PG8_WAIT_V(8); PG8_WAIT_L(0); PG8_BAR; PG8_MMA(0, 0, At, B0); PG8_MMA(0, 1, At, B1); PG8_BAR; PG8_SCHED;
	v_mfma_f32_16x16x32_bf16 v[60:63], v[126:129], v[166:169], v[60:63]
	v_mfma_f32_16x16x32_bf16 v[56:59], v[142:145], v[166:169], v[56:59]
	v_mfma_f32_16x16x32_bf16 v[44:47], v[126:129], v[174:177], v[44:47]
	v_mfma_f32_16x16x32_bf16 v[40:43], v[142:145], v[174:177], v[40:43]
	v_mfma_f32_16x16x32_bf16 v[28:31], v[126:129], v[194:197], v[28:31]
	v_mfma_f32_16x16x32_bf16 v[24:27], v[142:145], v[194:197], v[24:27]
	v_mfma_f32_16x16x32_bf16 v[12:15], v[126:129], v[202:205], v[12:15]
	v_mfma_f32_16x16x32_bf16 v[8:11], v[142:145], v[202:205], v[8:11]
	v_mfma_f32_16x16x32_bf16 v[60:63], v[130:133], v[170:173], v[60:63]
	v_mfma_f32_16x16x32_bf16 v[56:59], v[146:149], v[170:173], v[56:59]
	v_mfma_f32_16x16x32_bf16 v[44:47], v[130:133], v[178:181], v[44:47]
	v_mfma_f32_16x16x32_bf16 v[40:43], v[146:149], v[178:181], v[40:43]
	v_mfma_f32_16x16x32_bf16 v[28:31], v[130:133], v[198:201], v[28:31]
	v_mfma_f32_16x16x32_bf16 v[24:27], v[146:149], v[198:201], v[24:27]
	v_mfma_f32_16x16x32_bf16 v[12:15], v[130:133], v[206:209], v[12:15]
	v_mfma_f32_16x16x32_bf16 v[8:11], v[146:149], v[206:209], v[8:11]
	v_mfma_f32_16x16x32_bf16 v[52:55], v[150:153], v[166:169], v[52:55]
	v_mfma_f32_16x16x32_bf16 v[48:51], v[158:161], v[166:169], v[48:51]
	v_mfma_f32_16x16x32_bf16 v[36:39], v[150:153], v[174:177], v[36:39]
	v_mfma_f32_16x16x32_bf16 v[32:35], v[158:161], v[174:177], v[32:35]
	v_mfma_f32_16x16x32_bf16 v[20:23], v[150:153], v[194:197], v[20:23]
	v_mfma_f32_16x16x32_bf16 v[16:19], v[158:161], v[194:197], v[16:19]
	v_mfma_f32_16x16x32_bf16 v[4:7], v[150:153], v[202:205], v[4:7]
	v_mfma_f32_16x16x32_bf16 v[0:3], v[158:161], v[202:205], v[0:3]
	v_mfma_f32_16x16x32_bf16 v[52:55], v[154:157], v[170:173], v[52:55]
	v_mfma_f32_16x16x32_bf16 v[48:51], v[162:165], v[170:173], v[48:51]
	v_mfma_f32_16x16x32_bf16 v[36:39], v[154:157], v[178:181], v[36:39]
	v_mfma_f32_16x16x32_bf16 v[32:35], v[162:165], v[178:181], v[32:35]
	v_mfma_f32_16x16x32_bf16 v[20:23], v[154:157], v[198:201], v[20:23]
	v_mfma_f32_16x16x32_bf16 v[16:19], v[162:165], v[198:201], v[16:19]
	v_mfma_f32_16x16x32_bf16 v[4:7], v[154:157], v[206:209], v[4:7]
	v_mfma_f32_16x16x32_bf16 v[0:3], v[162:165], v[206:209], v[0:3]
	s_barrier
	s_setprio 0
	s_add_i32 s76, 0, 0x18000
	s_add_i32 s77, 0, 0x1c000
	v_add_u32_e32 v146, s76, v233
	v_add_u32_e32 v162, s77, v233
	ds_read_b128 v[126:129], v146
	ds_read_b128 v[130:133], v146 offset:1024
	ds_read_b128 v[142:145], v146 offset:2048
	ds_read_b128 v[146:149], v146 offset:3072
	ds_read_b128 v[150:153], v162
	ds_read_b128 v[154:157], v162 offset:1024
	ds_read_b128 v[158:161], v162 offset:2048
	ds_read_b128 v[162:165], v162 offset:3072
	s_add_u32 s50, s56, 0x160000
	s_addc_u32 s51, s57, 0
	s_mov_b32 m0, s64
	v_lshl_add_u64 v[218:219], s[50:51], 0, v[188:189]
	ds_read_b128 v[166:169], v236 offset:32768
	ds_read_b128 v[170:173], v236 offset:33792
	ds_read_b128 v[174:177], v236 offset:34816
	ds_read_b128 v[178:181], v236 offset:35840
	ds_read_b128 v[194:197], v236 offset:36864
	ds_read_b128 v[198:201], v236 offset:37888
	ds_read_b128 v[202:205], v236 offset:38912
	ds_read_b128 v[206:209], v236 offset:39936
	global_load_lds_dwordx4 v[218:219], off
	v_lshl_add_u64 v[218:219], s[50:51], 0, v[186:187]
	s_mov_b32 m0, s65
	s_nop 0
	global_load_lds_dwordx4 v[218:219], off
	s_waitcnt vmcnt(8)
	s_waitcnt lgkmcnt(0)
	s_setprio 1
	s_barrier
	v_mfma_f32_16x16x32_bf16 v[138:141], v[126:129], v[166:169], v[138:141]
	v_mfma_f32_16x16x32_bf16 v[134:137], v[142:145], v[166:169], v[134:137]
	v_mfma_f32_16x16x32_bf16 v[114:117], v[126:129], v[174:177], v[114:117]
	v_mfma_f32_16x16x32_bf16 v[110:113], v[142:145], v[174:177], v[110:113]
	v_mfma_f32_16x16x32_bf16 v[92:95], v[126:129], v[194:197], v[92:95]
	v_mfma_f32_16x16x32_bf16 v[88:91], v[142:145], v[194:197], v[88:91]
	v_mfma_f32_16x16x32_bf16 v[76:79], v[126:129], v[202:205], v[76:79]
	v_mfma_f32_16x16x32_bf16 v[72:75], v[142:145], v[202:205], v[72:75]
	v_mfma_f32_16x16x32_bf16 v[138:141], v[130:133], v[170:173], v[138:141]
	v_mfma_f32_16x16x32_bf16 v[134:137], v[146:149], v[170:173], v[134:137]
	v_mfma_f32_16x16x32_bf16 v[114:117], v[130:133], v[178:181], v[114:117]
	v_mfma_f32_16x16x32_bf16 v[110:113], v[146:149], v[178:181], v[110:113]
	v_mfma_f32_16x16x32_bf16 v[92:95], v[130:133], v[198:201], v[92:95]
	v_mfma_f32_16x16x32_bf16 v[88:91], v[146:149], v[198:201], v[88:91]
	v_mfma_f32_16x16x32_bf16 v[76:79], v[130:133], v[206:209], v[76:79]
	v_mfma_f32_16x16x32_bf16 v[72:75], v[146:149], v[206:209], v[72:75]
	v_mfma_f32_16x16x32_bf16 v[122:125], v[150:153], v[166:169], v[122:125]
	v_mfma_f32_16x16x32_bf16 v[118:121], v[158:161], v[166:169], v[118:121]
	v_mfma_f32_16x16x32_bf16 v[106:109], v[150:153], v[174:177], v[106:109]
	v_mfma_f32_16x16x32_bf16 v[102:105], v[158:161], v[174:177], v[102:105]
	v_mfma_f32_16x16x32_bf16 v[84:87], v[150:153], v[194:197], v[84:87]
	v_mfma_f32_16x16x32_bf16 v[80:83], v[158:161], v[194:197], v[80:83]
	v_mfma_f32_16x16x32_bf16 v[68:71], v[150:153], v[202:205], v[68:71]
	v_mfma_f32_16x16x32_bf16 v[64:67], v[158:161], v[202:205], v[64:67]
	v_mfma_f32_16x16x32_bf16 v[122:125], v[154:157], v[170:173], v[122:125]
	v_mfma_f32_16x16x32_bf16 v[118:121], v[162:165], v[170:173], v[118:121]
	v_mfma_f32_16x16x32_bf16 v[106:109], v[154:157], v[178:181], v[106:109]
	v_mfma_f32_16x16x32_bf16 v[102:105], v[162:165], v[178:181], v[102:105]
	v_mfma_f32_16x16x32_bf16 v[84:87], v[154:157], v[198:201], v[84:87]
	v_mfma_f32_16x16x32_bf16 v[80:83], v[162:165], v[198:201], v[80:83]
	v_mfma_f32_16x16x32_bf16 v[68:71], v[154:157], v[206:209], v[68:71]
	v_mfma_f32_16x16x32_bf16 v[64:67], v[162:165], v[206:209], v[64:67]
	s_barrier
; #define PG8_GAS __attribute__((address_space(1)))
; #define PG8_STAGE(bufoff, gbase, voff) do { _Pragma("unroll") for (int _i = 0; _i < 2; ++_i) \
;         __builtin_amdgcn_global_load_lds((const unsigned*)((const char*)(gbase) + (voff)[_i]), (PG8_LAS unsigned*)(lds + (bufoff) + ldsw + _i * 8192), 16, 0, 0); } while (0)
; #define PG8_LDA(dst, b, h) do { _Pragma("unroll") for (int m = 0; m < 4; ++m) _Pragma("unroll") for (int k = 0; k < 2; ++k) dst[m][k] = *(const PG8_LAS bf16x8*)(lds + PG8_SA(b, h) + aoff + m * 2048 + k * 1024); } while (0)
; #define PG8_MMA(ai, bj, At, Bt) do { __builtin_amdgcn_s_setprio(1); _Pragma("unroll") for (int m = 0; m < 4; ++m) _Pragma("unroll") for (int n = 0; n < 2; ++n) _Pragma("unroll") for (int k = 0; k < 2; ++k) \
;         acc[ai][bj][m][n] = __builtin_amdgcn_mfma_f32_16x16x32_bf16(Bt[n][k], At[m][k], acc[ai][bj][m][n], 0, 0, 0); __builtin_amdgcn_s_setprio(0); } while (0)
; #define PG8_WAIT_V(n) asm volatile("s_waitcnt vmcnt(" #n ")" ::: "memory")
; #define PG8_BAR __builtin_amdgcn_s_barrier()
;     __device__ __forceinline__ void operator()(const f32x4 (&acc)[2][2][4][2], const Unit& u, int wr, int wc, int fr, int fq) const {
;         const int row0 = u.pm * BM + wr * 64 + fr, col0 = u.pn * BM + wc * 32 + 8 * fq, lcol = u.pn * BM + (wc * 4 + fq) * 16;
; #pragma unroll
;         for (int ai = 0; ai < 2; ++ai) {
;             u32x4 L4[4], H4[4][2];
; #pragma unroll
;             for (int m = 0; m < 4; ++m) {
;                 const int row = row0 + ai * HALF + m * 16; const size_t off = (size_t)row * 2048 + col0, loff = (size_t)row * 2048 + lcol;
;                 L4[m] = *(const PG8_GAS u32x4*)(lin + loff); H4[m][0] = *(const PG8_GAS u32x4*)(hin + off); H4[m][1] = *(const PG8_GAS u32x4*)(hin + off + HALF);
;             }
; template <class Epi, class Sched, bool ALIGN_EPI = false, bool SP2 = false>
; __device__ __forceinline__ void gemm_phase(PG8_LAS unsigned char* lds, const Gemm g, const Sched& S, const Epi& E, const int tid) {
;     ...
;             PG8_WAIT_V(8); PG8_WAIT_L(0); PG8_BAR; PG8_MMA(0, 0, At, B0); PG8_MMA(0, 1, At, B1); PG8_BAR; PG8_SCHED;
;             PG8_LDA(At, 1, 1); PG8_STAGE(PG8_SB(1, 0), b3, voffB); PG8_STAGE(PG8_SB(1, 1), b3 + hstep, voffB); PG8_STAGE(PG8_SA(1, 0), a3, voffA);
;             PG8_WAIT_V(8); PG8_WAIT_L(0); PG8_BAR; PG8_MMA(1, 0, At, B0); PG8_MMA(1, 1, At, B1); PG8_BAR; PG8_SCHED;
	s_setprio 0
	s_add_i32 s50, s76, s59
	v_lshl_add_u64 v[210:211], v[210:211], 0, s[28:29]
	s_mov_b32 m0, s50
	ds_read_b128 v[166:169], v236 offset:49152
	ds_read_b128 v[170:173], v236 offset:50176
	ds_read_b128 v[174:177], v236 offset:51200
	ds_read_b128 v[178:181], v236 offset:52224
	ds_read_b128 v[194:197], v236 offset:53248
	ds_read_b128 v[198:201], v236 offset:54272
	ds_read_b128 v[202:205], v236 offset:55296
	ds_read_b128 v[206:209], v236 offset:56320
	global_load_lds_dwordx4 v[210:211], off
	s_add_i32 m0, s50, 0x2000
	s_add_u32 s50, s54, 0x160080
	v_lshl_add_u64 v[210:211], v[212:213], 0, s[28:29]
	s_addc_u32 s51, s55, 0
	s_add_i32 s54, s77, s59
	global_load_lds_dwordx4 v[210:211], off
	v_lshl_add_u64 v[210:211], s[50:51], 0, v[96:97]
	s_mov_b32 m0, s54
	s_nop 0
	global_load_lds_dwordx4 v[210:211], off
	v_lshl_add_u64 v[210:211], s[50:51], 0, v[98:99]
	s_add_i32 m0, s54, 0x2000
	s_nop 0
	global_load_lds_dwordx4 v[210:211], off
	v_lshl_add_u64 v[210:211], v[214:215], 0, s[28:29]
	s_mov_b32 m0, s63
	s_nop 0
	global_load_lds_dwordx4 v[210:211], off
	v_lshl_add_u64 v[210:211], v[216:217], 0, s[28:29]
	s_mov_b32 m0, s66
	s_nop 0
	global_load_lds_dwordx4 v[210:211], off
	s_waitcnt vmcnt(8)
	s_waitcnt lgkmcnt(0)
	s_setprio 1
	s_barrier
	v_mfma_f32_16x16x32_bf16 v[60:63], v[126:129], v[166:169], v[60:63]
	v_mfma_f32_16x16x32_bf16 v[56:59], v[142:145], v[166:169], v[56:59]
	v_mfma_f32_16x16x32_bf16 v[44:47], v[126:129], v[174:177], v[44:47]
	v_mfma_f32_16x16x32_bf16 v[40:43], v[142:145], v[174:177], v[40:43]
	v_mfma_f32_16x16x32_bf16 v[28:31], v[126:129], v[194:197], v[28:31]
	v_mfma_f32_16x16x32_bf16 v[24:27], v[142:145], v[194:197], v[24:27]
	v_mfma_f32_16x16x32_bf16 v[12:15], v[126:129], v[202:205], v[12:15]
	v_mfma_f32_16x16x32_bf16 v[8:11], v[142:145], v[202:205], v[8:11]
	v_mfma_f32_16x16x32_bf16 v[60:63], v[130:133], v[170:173], v[60:63]
	v_mfma_f32_16x16x32_bf16 v[56:59], v[146:149], v[170:173], v[56:59]
	v_mfma_f32_16x16x32_bf16 v[44:47], v[130:133], v[178:181], v[44:47]
	v_mfma_f32_16x16x32_bf16 v[40:43], v[146:149], v[178:181], v[40:43]
	v_mfma_f32_16x16x32_bf16 v[28:31], v[130:133], v[198:201], v[28:31]
	v_mfma_f32_16x16x32_bf16 v[24:27], v[146:149], v[198:201], v[24:27]
	v_mfma_f32_16x16x32_bf16 v[12:15], v[130:133], v[206:209], v[12:15]
	v_mfma_f32_16x16x32_bf16 v[8:11], v[146:149], v[206:209], v[8:11]
	v_mfma_f32_16x16x32_bf16 v[52:55], v[150:153], v[166:169], v[52:55]
	v_mfma_f32_16x16x32_bf16 v[48:51], v[158:161], v[166:169], v[48:51]
	v_mfma_f32_16x16x32_bf16 v[36:39], v[150:153], v[174:177], v[36:39]
	v_mfma_f32_16x16x32_bf16 v[32:35], v[158:161], v[174:177], v[32:35]
	v_mfma_f32_16x16x32_bf16 v[20:23], v[150:153], v[194:197], v[20:23]
	v_mfma_f32_16x16x32_bf16 v[16:19], v[158:161], v[194:197], v[16:19]
	v_mfma_f32_16x16x32_bf16 v[4:7], v[150:153], v[202:205], v[4:7]
	v_mfma_f32_16x16x32_bf16 v[0:3], v[158:161], v[202:205], v[0:3]
	v_mfma_f32_16x16x32_bf16 v[52:55], v[154:157], v[170:173], v[52:55]
	v_mfma_f32_16x16x32_bf16 v[48:51], v[162:165], v[170:173], v[48:51]
	v_mfma_f32_16x16x32_bf16 v[36:39], v[154:157], v[178:181], v[36:39]
	v_mfma_f32_16x16x32_bf16 v[32:35], v[162:165], v[178:181], v[32:35]
	v_mfma_f32_16x16x32_bf16 v[20:23], v[154:157], v[198:201], v[20:23]
	v_mfma_f32_16x16x32_bf16 v[16:19], v[162:165], v[198:201], v[16:19]
	v_mfma_f32_16x16x32_bf16 v[4:7], v[154:157], v[206:209], v[4:7]
	v_mfma_f32_16x16x32_bf16 v[0:3], v[162:165], v[206:209], v[0:3]
	s_barrier
	s_setprio 0
	s_add_i32 s75, s75, 2
	s_add_u32 s72, s72, 0x100
	s_addc_u32 s73, s73, 0
	s_cmpk_gt_u32 s75, 0x55
	s_mov_b64 s[50:51], s[52:53]
	s_cbranch_scc0 .LBB0_403
	v_and_b32_e32 v127, 64, v228
	v_xor_b32_e32 v126, 16, v228
	v_add_u32_e32 v127, 64, v127
	v_cmp_lt_i32_e32 vcc, v126, v127
	s_lshl_b32 s50, s70, 8
	v_lshl_add_u32 v198, s71, 8, v101
	v_cndmask_b32_e32 v126, v228, v126, vcc
	v_or_b32_e32 v194, s50, v235
	v_lshlrev_b32_e32 v238, 2, v126
	v_xor_b32_e32 v126, 32, v228
	v_or_b32_e32 v196, s50, v234
	v_ashrrev_i32_e32 v195, 31, v194
	v_cmp_lt_i32_e32 vcc, v126, v127
	v_ashrrev_i32_e32 v199, 31, v198
	v_ashrrev_i32_e32 v197, 31, v196
	v_cndmask_b32_e32 v126, v228, v126, vcc
	v_lshl_add_u64 v[202:203], s[34:35], 0, v[194:195]
	v_lshlrev_b64 v[216:217], 11, v[198:199]
	v_lshlrev_b32_e32 v237, 2, v126
	v_lshlrev_b64 v[218:219], 1, v[196:197]
	v_lshl_add_u64 v[126:127], v[202:203], 0, v[216:217]
	v_lshl_add_u64 v[200:201], s[30:31], 0, v[218:219]
	global_load_dwordx4 v[170:173], v[126:127], off
	v_lshlrev_b64 v[220:221], 12, v[198:199]
	v_lshl_add_u64 v[126:127], v[200:201], 0, v[220:221]
	global_load_dwordx4 v[178:181], v[126:127], off
	global_load_dwordx4 v[174:177], v[126:127], off offset:256
	v_or_b32_e32 v212, 16, v198
	v_ashrrev_i32_e32 v213, 31, v212
	v_lshlrev_b64 v[214:215], 11, v[212:213]
	v_lshl_add_u64 v[126:127], v[202:203], 0, v[214:215]
	v_or_b32_e32 v208, 32, v198
	global_load_dwordx4 v[158:161], v[126:127], off
	v_lshlrev_b64 v[126:127], 12, v[212:213]
	v_ashrrev_i32_e32 v209, 31, v208
	v_lshl_add_u64 v[126:127], v[200:201], 0, v[126:127]
	v_lshlrev_b64 v[210:211], 11, v[208:209]
	global_load_dwordx4 v[166:169], v[126:127], off
	global_load_dwordx4 v[162:165], v[126:127], off offset:256
	v_lshl_add_u64 v[126:127], v[202:203], 0, v[210:211]
	v_or_b32_e32 v204, 48, v198
	global_load_dwordx4 v[146:149], v[126:127], off
	v_lshlrev_b64 v[126:127], 12, v[208:209]
	v_ashrrev_i32_e32 v205, 31, v204
	v_lshl_add_u64 v[126:127], v[200:201], 0, v[126:127]
	v_lshlrev_b64 v[206:207], 11, v[204:205]
	v_lshlrev_b64 v[130:131], 12, v[204:205]
	global_load_dwordx4 v[154:157], v[126:127], off
	global_load_dwordx4 v[150:153], v[126:127], off offset:256
	v_lshl_add_u64 v[126:127], v[202:203], 0, v[206:207]
	v_lshl_add_u64 v[130:131], v[200:201], 0, v[130:131]
	global_load_dwordx4 v[126:129], v[126:127], off
	s_nop 0
	global_load_dwordx4 v[142:145], v[130:131], off
	s_nop 0
	global_load_dwordx4 v[130:133], v[130:131], off offset:256
	v_mov_b32_e32 v243, v136
	v_mov_b32_e32 v242, v140
	s_waitcnt vmcnt(0)
; #define PG8_GAS __attribute__((address_space(1)))
; __device__ __forceinline__ float e_x24(unsigned h16, unsigned l8) { return __uint_as_float(((h16 - (l8 >> 7)) << 16) | (l8 << 8)); }
;     __device__ __forceinline__ void operator()(const f32x4 (&acc)[2][2][4][2], const Unit& u, int wr, int wc, int fr, int fq) const {
;     ...
;             for (int m = 0; m < 4; ++m) {
;                 const int row = row0 + ai * HALF + m * 16; const size_t off = (size_t)row * 2048 + col0, loff = (size_t)row * 2048 + lcol; float ss = 0.f;
;                 const u32x4 l4 = L4[m];
;                 u32x4 lo4;
; #pragma unroll
;                 for (int bj = 0; bj < 2; ++bj) {
;                     const u32x4 h4 = H4[m][bj];
;                     u32x4 ho;
; #pragma unroll
;                     for (int j = 0; j < 4; ++j) {
;                         const unsigned lw = l4[2 * bj + (j >> 1)], lb0 = (lw >> (16 * (j & 1))) & 0xffu, lb1 = (lw >> (16 * (j & 1) + 8)) & 0xffu;
;                         const float x0 = e_x24(h4[j] & 0xffffu, lb0) + acc[ai][bj][m][j >> 1][2 * (j & 1)] * scale, x1 = e_x24(h4[j] >> 16, lb1) + acc[ai][bj][m][j >> 1][2 * (j & 1) + 1] * scale;
;                         const unsigned b0 = __float_as_uint(x0), b1 = __float_as_uint(x1);
;                         ho[j] = ((b0 + 0x8000u) >> 16) | ((b1 + 0x8000u) & 0xffff0000u);
;                         const unsigned nb = ((b0 >> 8) & 0xffu) | (b1 & 0xff00u);
;                         if ((j & 1) == 0) lo4[2 * bj + (j >> 1)] = nb; else lo4[2 * bj + (j >> 1)] |= nb << 16;
;                         ss += x0 * x0 + x1 * x1;
;                     }
;                     *(PG8_GAS u32x4*)(hout + off + bj * HALF) = ho;
	v_lshrrev_b32_sdwa v222, v229, v171 dst_sel:DWORD dst_unused:UNUSED_PAD src0_sel:DWORD src1_sel:BYTE_0
	v_lshrrev_b32_sdwa v223, v229, v170 dst_sel:DWORD dst_unused:UNUSED_PAD src0_sel:DWORD src1_sel:BYTE_0
	v_sub_u32_sdwa v224, v178, v223 dst_sel:WORD_1 dst_unused:UNUSED_PAD src0_sel:DWORD src1_sel:DWORD
	v_sub_u32_sdwa v222, v180, v222 dst_sel:WORD_1 dst_unused:UNUSED_PAD src0_sel:DWORD src1_sel:DWORD
	v_lshlrev_b32_sdwa v223, v230, v171 dst_sel:DWORD dst_unused:UNUSED_PAD src0_sel:DWORD src1_sel:BYTE_0
	v_lshlrev_b32_sdwa v225, v230, v170 dst_sel:DWORD dst_unused:UNUSED_PAD src0_sel:DWORD src1_sel:BYTE_0
	v_or_b32_e32 v223, v222, v223
	v_or_b32_e32 v222, v224, v225
	v_mov_b32_e32 v224, v138
	v_mov_b32_e32 v225, v134
	v_pk_fma_f32 v[222:223], v[224:225], 0.5, v[222:223] op_sel_hi:[1,0,1]
	v_lshlrev_b32_e32 v224, 1, v170
	v_add_u32_e32 v134, 0x8000, v222
	v_lshrrev_b32_e32 v138, 16, v134
	v_lshlrev_b32_e32 v134, 1, v171
	v_and_b32_e32 v134, 0x10000, v134
	v_and_b32_e32 v224, 0x10000, v224
	v_sub_u32_e32 v134, v180, v134
	v_sub_u32_e32 v178, v178, v224
	v_and_b32_e32 v134, 0xffff0000, v134
	v_and_b32_e32 v178, 0xffff0000, v178
	v_and_b32_e32 v180, 0xff00, v171
	v_and_b32_e32 v224, 0xff00, v170
	v_or_b32_e32 v225, v134, v180
	v_or_b32_e32 v224, v178, v224
	v_mov_b32_e32 v134, v139
	v_pk_fma_f32 v[224:225], v[134:135], 0.5, v[224:225] op_sel_hi:[1,0,1]
	v_and_b32_sdwa v135, v171, s93 dst_sel:DWORD dst_unused:UNUSED_PAD src0_sel:WORD_1 src1_sel:DWORD
	v_and_b32_sdwa v178, v170, s93 dst_sel:DWORD dst_unused:UNUSED_PAD src0_sel:WORD_1 src1_sel:DWORD
	v_lshlrev_b32_sdwa v239, v231, v170 dst_sel:DWORD dst_unused:UNUSED_PAD src0_sel:DWORD src1_sel:BYTE_3
	v_lshlrev_b32_sdwa v136, v231, v171 dst_sel:DWORD dst_unused:UNUSED_PAD src0_sel:DWORD src1_sel:BYTE_3
	v_lshrrev_b32_e32 v180, 7, v178
	v_lshrrev_b32_e32 v240, 7, v135
	v_and_b32_e32 v136, 0x10000, v136
	v_and_b32_e32 v140, 0x10000, v239
	v_sub_u32_sdwa v180, v179, v180 dst_sel:WORD_1 dst_unused:UNUSED_PAD src0_sel:DWORD src1_sel:DWORD
	v_sub_u32_sdwa v240, v181, v240 dst_sel:WORD_1 dst_unused:UNUSED_PAD src0_sel:DWORD src1_sel:DWORD
	v_lshlrev_b32_e32 v135, 8, v135
	v_lshlrev_b32_e32 v178, 8, v178
	v_sub_u32_e32 v136, v181, v136
	v_sub_u32_e32 v140, v179, v140
	v_or_b32_e32 v241, v240, v135
	v_or_b32_e32 v240, v180, v178
	v_and_b32_e32 v136, 0xffff0000, v136
	v_and_b32_e32 v140, 0xffff0000, v140
	v_lshlrev_b32_sdwa v171, v230, v171 dst_sel:DWORD dst_unused:UNUSED_PAD src0_sel:DWORD src1_sel:BYTE_3
	v_lshlrev_b32_sdwa v170, v230, v170 dst_sel:DWORD dst_unused:UNUSED_PAD src0_sel:DWORD src1_sel:BYTE_3
	v_pk_fma_f32 v[240:241], v[242:243], 0.5, v[240:241] op_sel_hi:[1,0,1]
	v_or_b32_e32 v171, v136, v171
	v_or_b32_e32 v170, v140, v170
	v_mov_b32_e32 v136, v141
	v_add_u32_e32 v135, 0x8000, v240
	v_pk_fma_f32 v[140:141], v[136:137], 0.5, v[170:171] op_sel_hi:[1,0,1]
	v_lshrrev_b32_e32 v135, 16, v135
	v_add_u32_e32 v136, 0x8000, v140
	v_and_or_b32 v135, v136, s90, v135
	v_pk_mul_f32 v[136:137], v[140:141], v[140:141]
	v_add_u32_e32 v178, 0x8000, v141
	v_pk_fma_f32 v[170:171], v[240:241], v[240:241], v[136:137]
	v_add_u32_e32 v136, 0x8000, v223
	v_lshrrev_b32_e32 v136, 16, v136
	v_add_u32_e32 v137, 0x8000, v225
	v_and_or_b32 v136, v137, s90, v136
	v_add_u32_e32 v137, 0x8000, v241
	v_lshrrev_b32_e32 v137, 16, v137
	v_add_u32_e32 v134, 0x8000, v224
	v_and_or_b32 v137, v178, s90, v137
	v_lshl_add_u64 v[178:179], s[30:31], 0, v[220:221]
	v_and_or_b32 v134, v134, s90, v138
	v_lshl_add_u64 v[178:179], v[178:179], 0, v[218:219]
	global_store_dwordx4 v[178:179], v[134:137], off
	v_lshlrev_b32_sdwa v220, v231, v172 dst_sel:DWORD dst_unused:UNUSED_PAD src0_sel:DWORD src1_sel:BYTE_3
	v_mov_b32_e32 v219, v120
	v_lshrrev_b32_sdwa v134, v229, v173 dst_sel:DWORD dst_unused:UNUSED_PAD src0_sel:DWORD src1_sel:BYTE_0
	v_lshrrev_b32_sdwa v135, v229, v172 dst_sel:DWORD dst_unused:UNUSED_PAD src0_sel:DWORD src1_sel:BYTE_0
	v_sub_u32_sdwa v136, v174, v135 dst_sel:WORD_1 dst_unused:UNUSED_PAD src0_sel:DWORD src1_sel:DWORD
	v_sub_u32_sdwa v134, v176, v134 dst_sel:WORD_1 dst_unused:UNUSED_PAD src0_sel:DWORD src1_sel:DWORD
	v_lshlrev_b32_sdwa v135, v230, v173 dst_sel:DWORD dst_unused:UNUSED_PAD src0_sel:DWORD src1_sel:BYTE_0
	v_lshlrev_b32_sdwa v137, v230, v172 dst_sel:DWORD dst_unused:UNUSED_PAD src0_sel:DWORD src1_sel:BYTE_0
	v_or_b32_e32 v135, v134, v135
	v_or_b32_e32 v134, v136, v137
	v_mov_b32_e32 v136, v122
	v_mov_b32_e32 v137, v118
	v_pk_fma_f32 v[134:135], v[136:137], 0.5, v[134:135] op_sel_hi:[1,0,1]
; #define PG8_GAS __attribute__((address_space(1)))
; __device__ __forceinline__ float e_x24(unsigned h16, unsigned l8) { return __uint_as_float(((h16 - (l8 >> 7)) << 16) | (l8 << 8)); }
;     __device__ __forceinline__ void operator()(const f32x4 (&acc)[2][2][4][2], const Unit& u, int wr, int wc, int fr, int fq) const {
;     ...
;                     for (int j = 0; j < 4; ++j) {
;                         const unsigned lw = l4[2 * bj + (j >> 1)], lb0 = (lw >> (16 * (j & 1))) & 0xffu, lb1 = (lw >> (16 * (j & 1) + 8)) & 0xffu;
;                         const float x0 = e_x24(h4[j] & 0xffffu, lb0) + acc[ai][bj][m][j >> 1][2 * (j & 1)] * scale, x1 = e_x24(h4[j] >> 16, lb1) + acc[ai][bj][m][j >> 1][2 * (j & 1) + 1] * scale;
;                         const unsigned b0 = __float_as_uint(x0), b1 = __float_as_uint(x1);
;                         ho[j] = ((b0 + 0x8000u) >> 16) | ((b1 + 0x8000u) & 0xffff0000u);
;                         const unsigned nb = ((b0 >> 8) & 0xffu) | (b1 & 0xff00u);
;                         if ((j & 1) == 0) lo4[2 * bj + (j >> 1)] = nb; else lo4[2 * bj + (j >> 1)] |= nb << 16;
;                         ss += x0 * x0 + x1 * x1;
;                     }
;                     *(PG8_GAS u32x4*)(hout + off + bj * HALF) = ho;
;                 }
;                 *(PG8_GAS u32x4*)(lout + loff) = lo4;
;                 ss += __shfl_xor(ss, 16); ss += __shfl_xor(ss, 32);
;                 if (fq == 0) __hip_atomic_fetch_add((PG8_GAS unsigned long long*)(rowsq_out + row), (unsigned long long)(ss * 16777216.0f + 0.5f), __ATOMIC_RELAXED, __HIP_MEMORY_SCOPE_AGENT);
	v_lshlrev_b32_e32 v122, 1, v172
	v_add_u32_e32 v118, 0x8000, v134
	v_lshrrev_b32_e32 v180, 16, v118
	v_lshlrev_b32_e32 v118, 1, v173
	v_and_b32_e32 v118, 0x10000, v118
	v_and_b32_e32 v122, 0x10000, v122
	v_sub_u32_e32 v118, v176, v118
	v_sub_u32_e32 v122, v174, v122
	v_and_b32_e32 v118, 0xffff0000, v118
	v_and_b32_e32 v122, 0xffff0000, v122
	v_and_b32_e32 v136, 0xff00, v173
	v_and_b32_e32 v174, 0xff00, v172
	v_or_b32_e32 v137, v118, v136
	v_or_b32_e32 v136, v122, v174
	v_mov_b32_e32 v118, v123
	v_pk_fma_f32 v[122:123], v[118:119], 0.5, v[136:137] op_sel_hi:[1,0,1]
	v_and_b32_sdwa v119, v173, s93 dst_sel:DWORD dst_unused:UNUSED_PAD src0_sel:WORD_1 src1_sel:DWORD
	v_add_u32_e32 v118, 0x8000, v122
	v_and_b32_sdwa v174, v172, s93 dst_sel:DWORD dst_unused:UNUSED_PAD src0_sel:WORD_1 src1_sel:DWORD
	v_lshlrev_b32_sdwa v120, v231, v173 dst_sel:DWORD dst_unused:UNUSED_PAD src0_sel:DWORD src1_sel:BYTE_3
	v_and_or_b32 v118, v118, s90, v180
	v_lshrrev_b32_e32 v176, 7, v174
	v_lshrrev_b32_e32 v180, 7, v119
	v_mov_b32_e32 v218, v124
	v_and_b32_e32 v120, 0x10000, v120
	v_and_b32_e32 v124, 0x10000, v220
	v_sub_u32_sdwa v176, v175, v176 dst_sel:WORD_1 dst_unused:UNUSED_PAD src0_sel:DWORD src1_sel:DWORD
	v_sub_u32_sdwa v180, v177, v180 dst_sel:WORD_1 dst_unused:UNUSED_PAD src0_sel:DWORD src1_sel:DWORD
	v_lshlrev_b32_e32 v119, 8, v119
	v_lshlrev_b32_e32 v174, 8, v174
	v_sub_u32_e32 v120, v177, v120
	v_sub_u32_e32 v124, v175, v124
	v_or_b32_e32 v181, v180, v119
	v_or_b32_e32 v180, v176, v174
	v_and_b32_e32 v120, 0xffff0000, v120
	v_and_b32_e32 v124, 0xffff0000, v124
	v_lshlrev_b32_sdwa v173, v230, v173 dst_sel:DWORD dst_unused:UNUSED_PAD src0_sel:DWORD src1_sel:BYTE_3
	v_lshlrev_b32_sdwa v172, v230, v172 dst_sel:DWORD dst_unused:UNUSED_PAD src0_sel:DWORD src1_sel:BYTE_3
	v_pk_fma_f32 v[180:181], v[218:219], 0.5, v[180:181] op_sel_hi:[1,0,1]
	v_or_b32_e32 v173, v120, v173
	v_or_b32_e32 v172, v124, v172
	v_mov_b32_e32 v120, v125
	v_add_u32_e32 v119, 0x8000, v180
	v_pk_fma_f32 v[124:125], v[120:121], 0.5, v[172:173] op_sel_hi:[1,0,1]
	v_lshrrev_b32_e32 v119, 16, v119
	v_add_u32_e32 v120, 0x8000, v124
	v_pk_mul_f32 v[138:139], v[224:225], v[224:225]
	v_pk_mul_f32 v[136:137], v[122:123], v[122:123]
	v_and_or_b32 v119, v120, s90, v119
	v_pk_mul_f32 v[120:121], v[124:125], v[124:125]
	v_pk_fma_f32 v[138:139], v[222:223], v[222:223], v[138:139]
	v_pk_fma_f32 v[136:137], v[134:135], v[134:135], v[136:137]
	v_pk_fma_f32 v[172:173], v[180:181], v[180:181], v[120:121]
	v_add_u32_e32 v120, 0x8000, v135
	v_lshrrev_b32_e32 v134, 8, v134
	v_lshrrev_b32_e32 v120, 16, v120
	v_add_u32_e32 v121, 0x8000, v123
	v_perm_b32 v122, v122, v134, s94
	v_add_f32_e32 v134, v138, v170
	v_and_or_b32 v120, v121, s90, v120
	v_add_u32_e32 v121, 0x8000, v181
	v_add_f32_e32 v134, v139, v134
	v_lshrrev_b32_e32 v121, 16, v121
	v_add_u32_e32 v174, 0x8000, v125
	v_add_f32_e32 v134, v171, v134
	v_and_or_b32 v121, v174, s90, v121
	v_lshrrev_b32_e32 v174, 8, v181
	v_lshrrev_b32_e32 v175, 8, v180
	v_add_f32_e32 v134, v136, v134
	v_lshrrev_b32_e32 v176, 8, v241
	v_lshrrev_b32_e32 v177, 8, v240
	v_perm_b32 v124, v124, v175, s94
	v_perm_b32 v125, v125, v174, s94
	v_lshrrev_b32_e32 v135, 8, v135
	v_lshrrev_b32_e32 v174, 8, v223
	v_lshrrev_b32_e32 v175, 8, v222
	v_add_f32_e32 v134, v172, v134
	v_perm_b32 v140, v140, v177, s94
	v_perm_b32 v141, v141, v176, s94
	v_perm_b32 v175, v224, v175, s94
	v_perm_b32 v174, v225, v174, s94
	v_perm_b32 v123, v123, v135, s94
	v_add_f32_e32 v134, v137, v134
	global_store_dwordx4 v[178:179], v[118:121], off offset:256
	v_lshl_or_b32 v125, v125, 16, v123
	v_lshl_or_b32 v124, v124, 16, v122
	v_lshl_add_u64 v[118:119], s[34:35], 0, v[216:217]
	v_lshl_or_b32 v123, v141, 16, v174
	v_lshl_or_b32 v122, v140, 16, v175
	v_add_f32_e32 v134, v173, v134
	v_lshl_add_u64 v[118:119], v[118:119], 0, v[194:195]
	global_store_dwordx4 v[118:119], v[122:125], off
	ds_bpermute_b32 v118, v238, v134
	s_waitcnt lgkmcnt(0)
	v_add_f32_e32 v118, v134, v118
	ds_bpermute_b32 v119, v237, v118
	s_and_saveexec_b64 s[50:51], s[40:41]
	s_cbranch_execz .LBB0_406
	s_waitcnt lgkmcnt(0)
	v_add_f32_e32 v118, v118, v119
	v_fma_f32 v118, v118, s80, 0.5
	v_trunc_f32_e32 v118, v118
	v_mul_f32_e32 v119, 0x2f800000, v118
	v_floor_f32_e32 v119, v119
	v_fmac_f32_e32 v118, 0xcf800000, v119
	v_cvt_u32_f32_e32 v118, v118
	v_cvt_u32_f32_e32 v119, v119
	v_lshl_add_u64 v[120:121], v[198:199], 3, s[48:49]
	global_atomic_add_x2 v[120:121], v[118:119], off

; #define PG8_STAGE(bufoff, gbase, voff) do { _Pragma("unroll") for (int _i = 0; _i < 2; ++_i) \
;         __builtin_amdgcn_global_load_lds((const unsigned*)((const char*)(gbase) + (voff)[_i]), (PG8_LAS unsigned*)(lds + (bufoff) + ldsw + _i * 8192), 16, 0, 0); } while (0)
; #define PG8_LDA(dst, b, h) do { _Pragma("unroll") for (int m = 0; m < 4; ++m) _Pragma("unroll") for (int k = 0; k < 2; ++k) dst[m][k] = *(const PG8_LAS bf16x8*)(lds + PG8_SA(b, h) + aoff + m * 2048 + k * 1024); } while (0)
; #define PG8_LDB(dst, b, h) do { _Pragma("unroll") for (int n = 0; n < 2; ++n) _Pragma("unroll") for (int k = 0; k < 2; ++k) dst[n][k] = *(const PG8_LAS bf16x8*)(lds + PG8_SB(b, h) + boff + n * 2048 + k * 1024); } while (0)
; #define PG8_MMA(ai, bj, At, Bt) do { __builtin_amdgcn_s_setprio(1); _Pragma("unroll") for (int m = 0; m < 4; ++m) _Pragma("unroll") for (int n = 0; n < 2; ++n) _Pragma("unroll") for (int k = 0; k < 2; ++k) \
;         acc[ai][bj][m][n] = __builtin_amdgcn_mfma_f32_16x16x32_bf16(Bt[n][k], At[m][k], acc[ai][bj][m][n], 0, 0, 0); __builtin_amdgcn_s_setprio(0); } while (0)
; #define PG8_WAIT_V(n) asm volatile("s_waitcnt vmcnt(" #n ")" ::: "memory")
; #define PG8_WAIT_L(n) asm volatile("s_waitcnt lgkmcnt(" #n ")" ::: "memory")
; template <class Epi, class Sched, bool ALIGN_EPI = false, bool SP2 = false>
; __device__ __forceinline__ void gemm_phase(PG8_LAS unsigned char* lds, const Gemm g, const Sched& S, const Epi& E, const int tid) {
;     ...
;             const bool last = (t == nt - 2);
;             const char* a1 = cA + (size_t)(t + 1) * kstep;
;             const char* a2 = last ? nA : cA + (size_t)(t + 2) * kstep; const char* b2 = last ? nB : cB + (size_t)(t + 2) * kstep;
;             const char* a3 = a2 + kstep; const char* b3 = b2 + kstep;
;             if (last && has_next) S.a_ready(nxt);
;             if constexpr (SP2) {
;             PG8_LDB(B0, 0, 0); PG8_LDB(B1, 0, 1); PG8_SCHED; PG8_LDA(At, 0, 0); PG8_STAGE(PG8_SA(1, 1), a1 + hstep, voffA);
;             PG8_WAIT_V(8); PG8_WAIT_L(0); PG8_BAR; PG8_MMA(0, 0, At, B0); PG8_MMA(0, 1, At, B1); PG8_BAR; PG8_SCHED;
;             PG8_LDA(At, 0, 1); PG8_STAGE(PG8_SB(0, 0), b2, voffB); PG8_STAGE(PG8_SB(0, 1), b2 + hstep, voffB); PG8_STAGE(PG8_SA(0, 0), a2, voffA);
;             PG8_WAIT_V(8); PG8_WAIT_L(0); PG8_BAR; PG8_MMA(1, 0, At, B0); PG8_MMA(1, 1, At, B1); PG8_BAR; PG8_SCHED;
.LBB0_488:
	s_add_u32 s58, s42, 0xfff80080
	s_addc_u32 s59, s43, -1
	s_add_i32 s78, 0, 0x10000
	s_cmp_eq_u32 s77, 28
	s_cselect_b32 s61, s53, s59
	s_cselect_b32 s60, s72, s58
	s_cselect_b32 s59, s51, s76
	s_cselect_b32 s58, s73, s75
	s_add_i32 s80, 0, 0x14000
	v_add_u32_e32 v156, s78, v163
	v_add_u32_e32 v160, s80, v163
	ds_read_b128 v[144:147], v156
	ds_read_b128 v[148:151], v156 offset:1024
	ds_read_b128 v[152:155], v156 offset:2048
	ds_read_b128 v[156:159], v156 offset:3072
	ds_read_b128 v[166:169], v160
	ds_read_b128 v[170:173], v160 offset:1024
	ds_read_b128 v[174:177], v160 offset:2048
	ds_read_b128 v[178:181], v160 offset:3072
	v_lshl_add_u64 v[160:161], s[42:43], 0, v[142:143]
	s_add_i32 m0, s63, 0xc000
	ds_read_b128 v[186:189], v165
	ds_read_b128 v[190:193], v165 offset:1024
	ds_read_b128 v[194:197], v165 offset:2048
	ds_read_b128 v[198:201], v165 offset:3072
	ds_read_b128 v[202:205], v165 offset:4096
	ds_read_b128 v[206:209], v165 offset:5120
	ds_read_b128 v[210:213], v165 offset:6144
	ds_read_b128 v[214:217], v165 offset:7168
	global_load_lds_dwordx4 v[160:161], off
	v_lshl_add_u64 v[160:161], s[42:43], 0, v[140:141]
	s_add_i32 m0, s63, 0xe000
	s_nop 0
	global_load_lds_dwordx4 v[160:161], off
	s_waitcnt vmcnt(8)
	s_waitcnt lgkmcnt(0)
	s_setprio 1
	s_barrier
	v_mfma_f32_16x16x32_bf16 v[122:125], v[144:147], v[186:189], v[122:125]
	v_mfma_f32_16x16x32_bf16 v[118:121], v[152:155], v[186:189], v[118:121]
	v_mfma_f32_16x16x32_bf16 v[110:113], v[144:147], v[194:197], v[110:113]
	v_mfma_f32_16x16x32_bf16 v[106:109], v[152:155], v[194:197], v[106:109]
	v_mfma_f32_16x16x32_bf16 v[88:91], v[144:147], v[202:205], v[88:91]
	v_mfma_f32_16x16x32_bf16 v[84:87], v[152:155], v[202:205], v[84:87]
	v_mfma_f32_16x16x32_bf16 v[72:75], v[144:147], v[210:213], v[72:75]
	v_mfma_f32_16x16x32_bf16 v[68:71], v[152:155], v[210:213], v[68:71]
	v_mfma_f32_16x16x32_bf16 v[122:125], v[148:151], v[190:193], v[122:125]
	v_mfma_f32_16x16x32_bf16 v[118:121], v[156:159], v[190:193], v[118:121]
	v_mfma_f32_16x16x32_bf16 v[110:113], v[148:151], v[198:201], v[110:113]
	v_mfma_f32_16x16x32_bf16 v[106:109], v[156:159], v[198:201], v[106:109]
	v_mfma_f32_16x16x32_bf16 v[88:91], v[148:151], v[206:209], v[88:91]
	v_mfma_f32_16x16x32_bf16 v[84:87], v[156:159], v[206:209], v[84:87]
	v_mfma_f32_16x16x32_bf16 v[72:75], v[148:151], v[214:217], v[72:75]
	v_mfma_f32_16x16x32_bf16 v[68:71], v[156:159], v[214:217], v[68:71]
	v_mfma_f32_16x16x32_bf16 v[130:133], v[166:169], v[186:189], v[130:133]
	v_mfma_f32_16x16x32_bf16 v[126:129], v[174:177], v[186:189], v[126:129]
	v_mfma_f32_16x16x32_bf16 v[114:117], v[166:169], v[194:197], v[114:117]
	v_mfma_f32_16x16x32_bf16 v[102:105], v[174:177], v[194:197], v[102:105]
	v_mfma_f32_16x16x32_bf16 v[92:95], v[166:169], v[202:205], v[92:95]
	v_mfma_f32_16x16x32_bf16 v[80:83], v[174:177], v[202:205], v[80:83]
	v_mfma_f32_16x16x32_bf16 v[76:79], v[166:169], v[210:213], v[76:79]
	v_mfma_f32_16x16x32_bf16 v[64:67], v[174:177], v[210:213], v[64:67]
	v_mfma_f32_16x16x32_bf16 v[130:133], v[170:173], v[190:193], v[130:133]
	v_mfma_f32_16x16x32_bf16 v[126:129], v[178:181], v[190:193], v[126:129]
	v_mfma_f32_16x16x32_bf16 v[114:117], v[170:173], v[198:201], v[114:117]
	v_mfma_f32_16x16x32_bf16 v[102:105], v[178:181], v[198:201], v[102:105]
	v_mfma_f32_16x16x32_bf16 v[92:95], v[170:173], v[206:209], v[92:95]
	v_mfma_f32_16x16x32_bf16 v[80:83], v[178:181], v[206:209], v[80:83]
	v_mfma_f32_16x16x32_bf16 v[76:79], v[170:173], v[214:217], v[76:79]
	v_mfma_f32_16x16x32_bf16 v[64:67], v[178:181], v[214:217], v[64:67]
	s_barrier
	s_setprio 0
	s_add_i32 s78, s78, s62
	v_lshl_add_u64 v[160:161], s[58:59], 0, v[96:97]
	s_mov_b32 m0, s78
	ds_read_b128 v[186:189], v165 offset:16384
	ds_read_b128 v[190:193], v165 offset:17408
	ds_read_b128 v[194:197], v165 offset:18432
	ds_read_b128 v[198:201], v165 offset:19456
	ds_read_b128 v[202:205], v165 offset:20480
	ds_read_b128 v[206:209], v165 offset:21504
	ds_read_b128 v[210:213], v165 offset:22528
	ds_read_b128 v[214:217], v165 offset:23552
	global_load_lds_dwordx4 v[160:161], off
	s_add_i32 m0, s78, 0x2000
	s_add_u32 s78, s58, 0x80000
	v_lshl_add_u64 v[218:219], s[58:59], 0, v[98:99]
	s_addc_u32 s79, s59, 0
	s_add_i32 s80, s80, s62
	global_load_lds_dwordx4 v[218:219], off
	v_lshl_add_u64 v[220:221], s[78:79], 0, v[96:97]
	s_mov_b32 m0, s80
	v_lshl_add_u64 v[222:223], s[60:61], 0, v[134:135]
	global_load_lds_dwordx4 v[220:221], off
	v_lshl_add_u64 v[220:221], s[78:79], 0, v[98:99]
	s_add_i32 m0, s80, 0x2000
	s_nop 0
	global_load_lds_dwordx4 v[220:221], off
	v_lshl_add_u64 v[220:221], s[60:61], 0, v[136:137]
	s_mov_b32 m0, s63
	s_nop 0
	global_load_lds_dwordx4 v[220:221], off
	s_mov_b32 m0, s64
	s_nop 0
	global_load_lds_dwordx4 v[222:223], off
	s_waitcnt vmcnt(8)
	s_waitcnt lgkmcnt(0)
	s_setprio 1
	s_barrier
; #define PG8_STAGE(bufoff, gbase, voff) do { _Pragma("unroll") for (int _i = 0; _i < 2; ++_i) \
;         __builtin_amdgcn_global_load_lds((const unsigned*)((const char*)(gbase) + (voff)[_i]), (PG8_LAS unsigned*)(lds + (bufoff) + ldsw + _i * 8192), 16, 0, 0); } while (0)
; #define PG8_LDA(dst, b, h) do { _Pragma("unroll") for (int m = 0; m < 4; ++m) _Pragma("unroll") for (int k = 0; k < 2; ++k) dst[m][k] = *(const PG8_LAS bf16x8*)(lds + PG8_SA(b, h) + aoff + m * 2048 + k * 1024); } while (0)
; #define PG8_LDB(dst, b, h) do { _Pragma("unroll") for (int n = 0; n < 2; ++n) _Pragma("unroll") for (int k = 0; k < 2; ++k) dst[n][k] = *(const PG8_LAS bf16x8*)(lds + PG8_SB(b, h) + boff + n * 2048 + k * 1024); } while (0)
; #define PG8_MMA(ai, bj, At, Bt) do { __builtin_amdgcn_s_setprio(1); _Pragma("unroll") for (int m = 0; m < 4; ++m) _Pragma("unroll") for (int n = 0; n < 2; ++n) _Pragma("unroll") for (int k = 0; k < 2; ++k) \
;         acc[ai][bj][m][n] = __builtin_amdgcn_mfma_f32_16x16x32_bf16(Bt[n][k], At[m][k], acc[ai][bj][m][n], 0, 0, 0); __builtin_amdgcn_s_setprio(0); } while (0)
; #define PG8_WAIT_V(n) asm volatile("s_waitcnt vmcnt(" #n ")" ::: "memory")
; #define PG8_WAIT_L(n) asm volatile("s_waitcnt lgkmcnt(" #n ")" ::: "memory")
; #define PG8_BAR __builtin_amdgcn_s_barrier()
; #define PG8_SCHED __builtin_amdgcn_sched_barrier(0)
; template <class Epi, class Sched, bool ALIGN_EPI = false, bool SP2 = false>
; __device__ __forceinline__ void gemm_phase(PG8_LAS unsigned char* lds, const Gemm g, const Sched& S, const Epi& E, const int tid) {
;     ...
;             PG8_WAIT_V(8); PG8_WAIT_L(0); PG8_BAR; PG8_MMA(0, 0, At, B0); PG8_MMA(0, 1, At, B1); PG8_BAR; PG8_SCHED;
;             PG8_LDA(At, 0, 1); PG8_STAGE(PG8_SB(0, 0), b2, voffB); PG8_STAGE(PG8_SB(0, 1), b2 + hstep, voffB); PG8_STAGE(PG8_SA(0, 0), a2, voffA);
;             PG8_WAIT_V(8); PG8_WAIT_L(0); PG8_BAR; PG8_MMA(1, 0, At, B0); PG8_MMA(1, 1, At, B1); PG8_BAR; PG8_SCHED;
;             PG8_LDB(B0, 1, 0); PG8_LDB(B1, 1, 1); PG8_SCHED; PG8_LDA(At, 1, 0); PG8_STAGE(PG8_SA(0, 1), a2 + hstep, voffA);
;             PG8_WAIT_V(8); PG8_WAIT_L(0); PG8_BAR; PG8_MMA(0, 0, At, B0); PG8_MMA(0, 1, At, B1); PG8_BAR; PG8_SCHED;
	v_mfma_f32_16x16x32_bf16 v[56:59], v[144:147], v[186:189], v[56:59]
	v_mfma_f32_16x16x32_bf16 v[52:55], v[152:155], v[186:189], v[52:55]
	v_mfma_f32_16x16x32_bf16 v[40:43], v[144:147], v[194:197], v[40:43]
	v_mfma_f32_16x16x32_bf16 v[36:39], v[152:155], v[194:197], v[36:39]
	v_mfma_f32_16x16x32_bf16 v[24:27], v[144:147], v[202:205], v[24:27]
	v_mfma_f32_16x16x32_bf16 v[20:23], v[152:155], v[202:205], v[20:23]
	v_mfma_f32_16x16x32_bf16 v[8:11], v[144:147], v[210:213], v[8:11]
	v_mfma_f32_16x16x32_bf16 v[4:7], v[152:155], v[210:213], v[4:7]
	v_mfma_f32_16x16x32_bf16 v[56:59], v[148:151], v[190:193], v[56:59]
	v_mfma_f32_16x16x32_bf16 v[52:55], v[156:159], v[190:193], v[52:55]
	v_mfma_f32_16x16x32_bf16 v[40:43], v[148:151], v[198:201], v[40:43]
	v_mfma_f32_16x16x32_bf16 v[36:39], v[156:159], v[198:201], v[36:39]
	v_mfma_f32_16x16x32_bf16 v[24:27], v[148:151], v[206:209], v[24:27]
	v_mfma_f32_16x16x32_bf16 v[20:23], v[156:159], v[206:209], v[20:23]
	v_mfma_f32_16x16x32_bf16 v[8:11], v[148:151], v[214:217], v[8:11]
	v_mfma_f32_16x16x32_bf16 v[4:7], v[156:159], v[214:217], v[4:7]
	v_mfma_f32_16x16x32_bf16 v[60:63], v[166:169], v[186:189], v[60:63]
	v_mfma_f32_16x16x32_bf16 v[48:51], v[174:177], v[186:189], v[48:51]
	v_mfma_f32_16x16x32_bf16 v[44:47], v[166:169], v[194:197], v[44:47]
	v_mfma_f32_16x16x32_bf16 v[32:35], v[174:177], v[194:197], v[32:35]
	v_mfma_f32_16x16x32_bf16 v[28:31], v[166:169], v[202:205], v[28:31]
	v_mfma_f32_16x16x32_bf16 v[16:19], v[174:177], v[202:205], v[16:19]
	v_mfma_f32_16x16x32_bf16 v[12:15], v[166:169], v[210:213], v[12:15]
	v_mfma_f32_16x16x32_bf16 v[0:3], v[174:177], v[210:213], v[0:3]
	v_mfma_f32_16x16x32_bf16 v[60:63], v[170:173], v[190:193], v[60:63]
	v_mfma_f32_16x16x32_bf16 v[48:51], v[178:181], v[190:193], v[48:51]
	v_mfma_f32_16x16x32_bf16 v[44:47], v[170:173], v[198:201], v[44:47]
	v_mfma_f32_16x16x32_bf16 v[32:35], v[178:181], v[198:201], v[32:35]
	v_mfma_f32_16x16x32_bf16 v[28:31], v[170:173], v[206:209], v[28:31]
	v_mfma_f32_16x16x32_bf16 v[16:19], v[178:181], v[206:209], v[16:19]
	v_mfma_f32_16x16x32_bf16 v[12:15], v[170:173], v[214:217], v[12:15]
	v_mfma_f32_16x16x32_bf16 v[0:3], v[178:181], v[214:217], v[0:3]
	s_barrier
	s_setprio 0
	s_add_i32 s78, 0, 0x18000
	s_add_i32 s79, 0, 0x1c000
	v_add_u32_e32 v156, s78, v163
	v_add_u32_e32 v162, s79, v163
	ds_read_b128 v[144:147], v156
	ds_read_b128 v[148:151], v156 offset:1024
	ds_read_b128 v[152:155], v156 offset:2048
	ds_read_b128 v[156:159], v156 offset:3072
	ds_read_b128 v[166:169], v162
	ds_read_b128 v[170:173], v162 offset:1024
	ds_read_b128 v[174:177], v162 offset:2048
	ds_read_b128 v[178:181], v162 offset:3072
	s_add_u32 s60, s60, 0x80000
	s_addc_u32 s61, s61, 0
	s_mov_b32 m0, s65
	v_lshl_add_u64 v[224:225], s[60:61], 0, v[136:137]
	ds_read_b128 v[186:189], v165 offset:32768
	ds_read_b128 v[190:193], v165 offset:33792
	ds_read_b128 v[194:197], v165 offset:34816
	ds_read_b128 v[198:201], v165 offset:35840
	ds_read_b128 v[202:205], v165 offset:36864
	ds_read_b128 v[206:209], v165 offset:37888
	ds_read_b128 v[210:213], v165 offset:38912
	ds_read_b128 v[214:217], v165 offset:39936
	global_load_lds_dwordx4 v[224:225], off
	v_lshl_add_u64 v[224:225], s[60:61], 0, v[134:135]
	s_mov_b32 m0, s66
	s_nop 0
	global_load_lds_dwordx4 v[224:225], off
	s_waitcnt vmcnt(8)
	s_waitcnt lgkmcnt(0)
	s_setprio 1
	s_barrier
	v_mfma_f32_16x16x32_bf16 v[122:125], v[144:147], v[186:189], v[122:125]
	v_mfma_f32_16x16x32_bf16 v[118:121], v[152:155], v[186:189], v[118:121]
	v_mfma_f32_16x16x32_bf16 v[110:113], v[144:147], v[194:197], v[110:113]
	v_mfma_f32_16x16x32_bf16 v[106:109], v[152:155], v[194:197], v[106:109]
	v_mfma_f32_16x16x32_bf16 v[88:91], v[144:147], v[202:205], v[88:91]
	v_mfma_f32_16x16x32_bf16 v[84:87], v[152:155], v[202:205], v[84:87]
	v_mfma_f32_16x16x32_bf16 v[72:75], v[144:147], v[210:213], v[72:75]
	v_mfma_f32_16x16x32_bf16 v[68:71], v[152:155], v[210:213], v[68:71]
	v_mfma_f32_16x16x32_bf16 v[122:125], v[148:151], v[190:193], v[122:125]
	v_mfma_f32_16x16x32_bf16 v[118:121], v[156:159], v[190:193], v[118:121]
	v_mfma_f32_16x16x32_bf16 v[110:113], v[148:151], v[198:201], v[110:113]
	v_mfma_f32_16x16x32_bf16 v[106:109], v[156:159], v[198:201], v[106:109]
	v_mfma_f32_16x16x32_bf16 v[88:91], v[148:151], v[206:209], v[88:91]
	v_mfma_f32_16x16x32_bf16 v[84:87], v[156:159], v[206:209], v[84:87]
	v_mfma_f32_16x16x32_bf16 v[72:75], v[148:151], v[214:217], v[72:75]
	v_mfma_f32_16x16x32_bf16 v[68:71], v[156:159], v[214:217], v[68:71]
	v_mfma_f32_16x16x32_bf16 v[130:133], v[166:169], v[186:189], v[130:133]
	v_mfma_f32_16x16x32_bf16 v[126:129], v[174:177], v[186:189], v[126:129]
	v_mfma_f32_16x16x32_bf16 v[114:117], v[166:169], v[194:197], v[114:117]
	v_mfma_f32_16x16x32_bf16 v[102:105], v[174:177], v[194:197], v[102:105]
	v_mfma_f32_16x16x32_bf16 v[92:95], v[166:169], v[202:205], v[92:95]
	v_mfma_f32_16x16x32_bf16 v[80:83], v[174:177], v[202:205], v[80:83]
	v_mfma_f32_16x16x32_bf16 v[76:79], v[166:169], v[210:213], v[76:79]
	v_mfma_f32_16x16x32_bf16 v[64:67], v[174:177], v[210:213], v[64:67]
	v_mfma_f32_16x16x32_bf16 v[130:133], v[170:173], v[190:193], v[130:133]
	v_mfma_f32_16x16x32_bf16 v[126:129], v[178:181], v[190:193], v[126:129]
	v_mfma_f32_16x16x32_bf16 v[114:117], v[170:173], v[198:201], v[114:117]
	v_mfma_f32_16x16x32_bf16 v[102:105], v[178:181], v[198:201], v[102:105]
	v_mfma_f32_16x16x32_bf16 v[92:95], v[170:173], v[206:209], v[92:95]
	v_mfma_f32_16x16x32_bf16 v[80:83], v[178:181], v[206:209], v[80:83]
	v_mfma_f32_16x16x32_bf16 v[76:79], v[170:173], v[214:217], v[76:79]
	v_mfma_f32_16x16x32_bf16 v[64:67], v[178:181], v[214:217], v[64:67]
	s_barrier
; #define PG8_STAGE(bufoff, gbase, voff) do { _Pragma("unroll") for (int _i = 0; _i < 2; ++_i) \
;         __builtin_amdgcn_global_load_lds((const unsigned*)((const char*)(gbase) + (voff)[_i]), (PG8_LAS unsigned*)(lds + (bufoff) + ldsw + _i * 8192), 16, 0, 0); } while (0)
; #define PG8_WAIT_V(n) asm volatile("s_waitcnt vmcnt(" #n ")" ::: "memory")
; #define PG8_WAIT_L(n) asm volatile("s_waitcnt lgkmcnt(" #n ")" ::: "memory")
; template <class Epi, class Sched, bool ALIGN_EPI = false, bool SP2 = false>
; __device__ __forceinline__ void gemm_phase(PG8_LAS unsigned char* lds, const Gemm g, const Sched& S, const Epi& E, const int tid) {
;     ...
;             PG8_WAIT_V(8); PG8_WAIT_L(0); PG8_BAR; PG8_MMA(0, 0, At, B0); PG8_MMA(0, 1, At, B1); PG8_BAR; PG8_SCHED;
;             PG8_LDA(At, 1, 1); PG8_STAGE(PG8_SB(1, 0), b3, voffB); PG8_STAGE(PG8_SB(1, 1), b3 + hstep, voffB); PG8_STAGE(PG8_SA(1, 0), a3, voffA);
;             PG8_WAIT_V(8); PG8_WAIT_L(0); PG8_BAR; PG8_MMA(1, 0, At, B0); PG8_MMA(1, 1, At, B1); PG8_BAR; PG8_SCHED;
;             } else {
;             PG8_LDB(B0, 0, 0); PG8_SCHED; PG8_LDA(At, 0, 0); PG8_STAGE(PG8_SA(1, 1), a1 + hstep, voffA);
;             PG8_WAIT_L(8); PG8_BAR; PG8_WAIT_L(0); PG8_MMA(0, 0, At, B0); PG8_BAR; PG8_SCHED;
;             PG8_LDB(B1, 0, 1); PG8_STAGE(PG8_SB(0, 0), b2, voffB);
;             PG8_BAR; PG8_WAIT_L(0); PG8_MMA(0, 1, At, B1); PG8_BAR;
;             PG8_LDA(At, 0, 1); PG8_STAGE(PG8_SA(0, 0), a2, voffA);
;             PG8_BAR; PG8_WAIT_L(0); PG8_MMA(1, 0, At, B0); PG8_BAR; PG8_SCHED;
;             PG8_STAGE(PG8_SB(0, 1), b2 + hstep, voffB);
;             PG8_WAIT_V(6); PG8_BAR; PG8_MMA(1, 1, At, B1); PG8_BAR;
;             PG8_LDB(B0, 1, 0); PG8_SCHED; PG8_LDA(At, 1, 0); PG8_STAGE(PG8_SA(0, 1), a2 + hstep, voffA);
;             PG8_WAIT_L(8); PG8_BAR; PG8_WAIT_L(0); PG8_MMA(0, 0, At, B0); PG8_BAR; PG8_SCHED;
;             PG8_LDB(B1, 1, 1); PG8_STAGE(PG8_SB(1, 0), b3, voffB);
;             PG8_BAR; PG8_WAIT_L(0); PG8_MMA(0, 1, At, B1); PG8_BAR;
;             PG8_LDA(At, 1, 1); PG8_STAGE(PG8_SA(1, 0), a3, voffA);
;             PG8_BAR; PG8_WAIT_L(0); PG8_MMA(1, 0, At, B0); PG8_BAR; PG8_SCHED;
;             PG8_STAGE(PG8_SB(1, 1), b3 + hstep, voffB);
;             PG8_WAIT_V(6); PG8_BAR; PG8_MMA(1, 1, At, B1); PG8_BAR;
;             }
;         }
;         if constexpr (ALIGN_EPI) { if (wr == 0) PG8_BAR; }
	s_setprio 0
	s_add_i32 s60, s78, s62
	v_lshl_add_u64 v[160:161], v[160:161], 0, s[28:29]
	s_mov_b32 m0, s60
	ds_read_b128 v[186:189], v165 offset:49152
	ds_read_b128 v[190:193], v165 offset:50176
	ds_read_b128 v[194:197], v165 offset:51200
	ds_read_b128 v[198:201], v165 offset:52224
	ds_read_b128 v[202:205], v165 offset:53248
	ds_read_b128 v[206:209], v165 offset:54272
	ds_read_b128 v[210:213], v165 offset:55296
	ds_read_b128 v[214:217], v165 offset:56320
	global_load_lds_dwordx4 v[160:161], off
	s_add_i32 m0, s60, 0x2000
	s_add_u32 s58, s58, 0x80080
	v_lshl_add_u64 v[160:161], v[218:219], 0, s[28:29]
	s_addc_u32 s59, s59, 0
	s_add_i32 s60, s79, s62
	global_load_lds_dwordx4 v[160:161], off
	v_lshl_add_u64 v[160:161], s[58:59], 0, v[96:97]
	s_mov_b32 m0, s60
	s_nop 0
	global_load_lds_dwordx4 v[160:161], off
	v_lshl_add_u64 v[160:161], s[58:59], 0, v[98:99]
	s_add_i32 m0, s60, 0x2000
	s_nop 0
	global_load_lds_dwordx4 v[160:161], off
	v_lshl_add_u64 v[160:161], v[220:221], 0, s[28:29]
	s_mov_b32 m0, s67
	s_nop 0
	global_load_lds_dwordx4 v[160:161], off
	v_lshl_add_u64 v[160:161], v[222:223], 0, s[28:29]
	s_mov_b32 m0, s68
	s_nop 0
	global_load_lds_dwordx4 v[160:161], off
	s_waitcnt vmcnt(8)
	s_waitcnt lgkmcnt(0)
	s_setprio 1
	s_barrier
	v_mfma_f32_16x16x32_bf16 v[56:59], v[144:147], v[186:189], v[56:59]
	v_mfma_f32_16x16x32_bf16 v[52:55], v[152:155], v[186:189], v[52:55]
	v_mfma_f32_16x16x32_bf16 v[40:43], v[144:147], v[194:197], v[40:43]
	v_mfma_f32_16x16x32_bf16 v[36:39], v[152:155], v[194:197], v[36:39]
	v_mfma_f32_16x16x32_bf16 v[24:27], v[144:147], v[202:205], v[24:27]
	v_mfma_f32_16x16x32_bf16 v[20:23], v[152:155], v[202:205], v[20:23]
	v_mfma_f32_16x16x32_bf16 v[8:11], v[144:147], v[210:213], v[8:11]
	v_mfma_f32_16x16x32_bf16 v[4:7], v[152:155], v[210:213], v[4:7]
	v_mfma_f32_16x16x32_bf16 v[56:59], v[148:151], v[190:193], v[56:59]
	v_mfma_f32_16x16x32_bf16 v[52:55], v[156:159], v[190:193], v[52:55]
	v_mfma_f32_16x16x32_bf16 v[40:43], v[148:151], v[198:201], v[40:43]
	v_mfma_f32_16x16x32_bf16 v[36:39], v[156:159], v[198:201], v[36:39]
	v_mfma_f32_16x16x32_bf16 v[24:27], v[148:151], v[206:209], v[24:27]
	v_mfma_f32_16x16x32_bf16 v[20:23], v[156:159], v[206:209], v[20:23]
	v_mfma_f32_16x16x32_bf16 v[8:11], v[148:151], v[214:217], v[8:11]
	v_mfma_f32_16x16x32_bf16 v[4:7], v[156:159], v[214:217], v[4:7]
	v_mfma_f32_16x16x32_bf16 v[60:63], v[166:169], v[186:189], v[60:63]
	v_mfma_f32_16x16x32_bf16 v[48:51], v[174:177], v[186:189], v[48:51]
	v_mfma_f32_16x16x32_bf16 v[44:47], v[166:169], v[194:197], v[44:47]
	v_mfma_f32_16x16x32_bf16 v[32:35], v[174:177], v[194:197], v[32:35]
	v_mfma_f32_16x16x32_bf16 v[28:31], v[166:169], v[202:205], v[28:31]
	v_mfma_f32_16x16x32_bf16 v[16:19], v[174:177], v[202:205], v[16:19]
	v_mfma_f32_16x16x32_bf16 v[12:15], v[166:169], v[210:213], v[12:15]
	v_mfma_f32_16x16x32_bf16 v[0:3], v[174:177], v[210:213], v[0:3]
	v_mfma_f32_16x16x32_bf16 v[60:63], v[170:173], v[190:193], v[60:63]
	v_mfma_f32_16x16x32_bf16 v[48:51], v[178:181], v[190:193], v[48:51]
	v_mfma_f32_16x16x32_bf16 v[44:47], v[170:173], v[198:201], v[44:47]
	v_mfma_f32_16x16x32_bf16 v[32:35], v[178:181], v[198:201], v[32:35]
	v_mfma_f32_16x16x32_bf16 v[28:31], v[170:173], v[206:209], v[28:31]
	v_mfma_f32_16x16x32_bf16 v[16:19], v[178:181], v[206:209], v[16:19]
	v_mfma_f32_16x16x32_bf16 v[12:15], v[170:173], v[214:217], v[12:15]
	v_mfma_f32_16x16x32_bf16 v[0:3], v[178:181], v[214:217], v[0:3]
	s_barrier
	s_setprio 0
	s_add_i32 s77, s77, 2
	s_add_u32 s75, s75, 0x100
	s_addc_u32 s76, s76, 0
	s_add_u32 s42, s42, 0x100
	s_addc_u32 s43, s43, 0
	s_cmp_gt_u32 s77, 29
	s_cbranch_scc0 .LBB0_488
	s_and_b64 vcc, exec, s[46:47]
	s_cbranch_vccz .LBB0_491
	s_barrier

; #define PG8_STAGE(bufoff, gbase, voff) do { _Pragma("unroll") for (int _i = 0; _i < 2; ++_i) \
;         __builtin_amdgcn_global_load_lds((const unsigned*)((const char*)(gbase) + (voff)[_i]), (PG8_LAS unsigned*)(lds + (bufoff) + ldsw + _i * 8192), 16, 0, 0); } while (0)
; #define PG8_LDA(dst, b, h) do { _Pragma("unroll") for (int m = 0; m < 4; ++m) _Pragma("unroll") for (int k = 0; k < 2; ++k) dst[m][k] = *(const PG8_LAS bf16x8*)(lds + PG8_SA(b, h) + aoff + m * 2048 + k * 1024); } while (0)
; #define PG8_LDB(dst, b, h) do { _Pragma("unroll") for (int n = 0; n < 2; ++n) _Pragma("unroll") for (int k = 0; k < 2; ++k) dst[n][k] = *(const PG8_LAS bf16x8*)(lds + PG8_SB(b, h) + boff + n * 2048 + k * 1024); } while (0)
; #define PG8_MMA(ai, bj, At, Bt) do { __builtin_amdgcn_s_setprio(1); _Pragma("unroll") for (int m = 0; m < 4; ++m) _Pragma("unroll") for (int n = 0; n < 2; ++n) _Pragma("unroll") for (int k = 0; k < 2; ++k) \
;         acc[ai][bj][m][n] = __builtin_amdgcn_mfma_f32_16x16x32_bf16(Bt[n][k], At[m][k], acc[ai][bj][m][n], 0, 0, 0); __builtin_amdgcn_s_setprio(0); } while (0)
; #define PG8_WAIT_V(n) asm volatile("s_waitcnt vmcnt(" #n ")" ::: "memory")
; #define PG8_WAIT_L(n) asm volatile("s_waitcnt lgkmcnt(" #n ")" ::: "memory")
; template <class Epi, class Sched, bool ALIGN_EPI = false, bool SP2 = false>
; __device__ __forceinline__ void gemm_phase(PG8_LAS unsigned char* lds, const Gemm g, const Sched& S, const Epi& E, const int tid) {
;     ...
;             const bool last = (t == nt - 2);
;             const char* a1 = cA + (size_t)(t + 1) * kstep;
;             const char* a2 = last ? nA : cA + (size_t)(t + 2) * kstep; const char* b2 = last ? nB : cB + (size_t)(t + 2) * kstep;
;             const char* a3 = a2 + kstep; const char* b3 = b2 + kstep;
;             if (last && has_next) S.a_ready(nxt);
;             if constexpr (SP2) {
;             PG8_LDB(B0, 0, 0); PG8_LDB(B1, 0, 1); PG8_SCHED; PG8_LDA(At, 0, 0); PG8_STAGE(PG8_SA(1, 1), a1 + hstep, voffA);
;             PG8_WAIT_V(8); PG8_WAIT_L(0); PG8_BAR; PG8_MMA(0, 0, At, B0); PG8_MMA(0, 1, At, B1); PG8_BAR; PG8_SCHED;
;             PG8_LDA(At, 0, 1); PG8_STAGE(PG8_SB(0, 0), b2, voffB); PG8_STAGE(PG8_SB(0, 1), b2 + hstep, voffB); PG8_STAGE(PG8_SA(0, 0), a2, voffA);
;             PG8_WAIT_V(8); PG8_WAIT_L(0); PG8_BAR; PG8_MMA(1, 0, At, B0); PG8_MMA(1, 1, At, B1); PG8_BAR; PG8_SCHED;
.LBB0_1199:
	s_add_u32 s56, s54, 0xfff80080
	s_addc_u32 s57, s55, -1
	s_add_i32 s77, 0, 0x10000
	s_cmp_eq_u32 s76, 28
	s_cselect_b32 s59, s49, s57
	s_cselect_b32 s58, s71, s56
	s_cselect_b32 s57, s47, s75
	s_cselect_b32 s56, s72, s73
	s_add_i32 s80, 0, 0x14000
	v_add_u32_e32 v146, s77, v233
	v_add_u32_e32 v162, s80, v233
	ds_read_b128 v[126:129], v146
	ds_read_b128 v[130:133], v146 offset:1024
	ds_read_b128 v[142:145], v146 offset:2048
	ds_read_b128 v[146:149], v146 offset:3072
	ds_read_b128 v[150:153], v162
	ds_read_b128 v[154:157], v162 offset:1024
	ds_read_b128 v[158:161], v162 offset:2048
	ds_read_b128 v[162:165], v162 offset:3072
	v_lshl_add_u64 v[210:211], s[54:55], 0, v[192:193]
	s_add_i32 m0, s62, 0xc000
	ds_read_b128 v[166:169], v236
	ds_read_b128 v[170:173], v236 offset:1024
	ds_read_b128 v[174:177], v236 offset:2048
	ds_read_b128 v[178:181], v236 offset:3072
	ds_read_b128 v[194:197], v236 offset:4096
	ds_read_b128 v[198:201], v236 offset:5120
	ds_read_b128 v[202:205], v236 offset:6144
	ds_read_b128 v[206:209], v236 offset:7168
	global_load_lds_dwordx4 v[210:211], off
	v_lshl_add_u64 v[210:211], s[54:55], 0, v[190:191]
	s_add_i32 m0, s62, 0xe000
	s_nop 0
	global_load_lds_dwordx4 v[210:211], off
	s_waitcnt vmcnt(8)
	s_waitcnt lgkmcnt(0)
	s_setprio 1
	s_barrier
	v_mfma_f32_16x16x32_bf16 v[138:141], v[126:129], v[166:169], v[138:141]
	v_mfma_f32_16x16x32_bf16 v[134:137], v[142:145], v[166:169], v[134:137]
	v_mfma_f32_16x16x32_bf16 v[114:117], v[126:129], v[174:177], v[114:117]
	v_mfma_f32_16x16x32_bf16 v[110:113], v[142:145], v[174:177], v[110:113]
	v_mfma_f32_16x16x32_bf16 v[92:95], v[126:129], v[194:197], v[92:95]
	v_mfma_f32_16x16x32_bf16 v[88:91], v[142:145], v[194:197], v[88:91]
	v_mfma_f32_16x16x32_bf16 v[76:79], v[126:129], v[202:205], v[76:79]
	v_mfma_f32_16x16x32_bf16 v[72:75], v[142:145], v[202:205], v[72:75]
	v_mfma_f32_16x16x32_bf16 v[138:141], v[130:133], v[170:173], v[138:141]
	v_mfma_f32_16x16x32_bf16 v[134:137], v[146:149], v[170:173], v[134:137]
	v_mfma_f32_16x16x32_bf16 v[114:117], v[130:133], v[178:181], v[114:117]
	v_mfma_f32_16x16x32_bf16 v[110:113], v[146:149], v[178:181], v[110:113]
	v_mfma_f32_16x16x32_bf16 v[92:95], v[130:133], v[198:201], v[92:95]
	v_mfma_f32_16x16x32_bf16 v[88:91], v[146:149], v[198:201], v[88:91]
	v_mfma_f32_16x16x32_bf16 v[76:79], v[130:133], v[206:209], v[76:79]
	v_mfma_f32_16x16x32_bf16 v[72:75], v[146:149], v[206:209], v[72:75]
	v_mfma_f32_16x16x32_bf16 v[122:125], v[150:153], v[166:169], v[122:125]
	v_mfma_f32_16x16x32_bf16 v[118:121], v[158:161], v[166:169], v[118:121]
	v_mfma_f32_16x16x32_bf16 v[106:109], v[150:153], v[174:177], v[106:109]
	v_mfma_f32_16x16x32_bf16 v[102:105], v[158:161], v[174:177], v[102:105]
	v_mfma_f32_16x16x32_bf16 v[84:87], v[150:153], v[194:197], v[84:87]
	v_mfma_f32_16x16x32_bf16 v[80:83], v[158:161], v[194:197], v[80:83]
	v_mfma_f32_16x16x32_bf16 v[68:71], v[150:153], v[202:205], v[68:71]
	v_mfma_f32_16x16x32_bf16 v[64:67], v[158:161], v[202:205], v[64:67]
	v_mfma_f32_16x16x32_bf16 v[122:125], v[154:157], v[170:173], v[122:125]
	v_mfma_f32_16x16x32_bf16 v[118:121], v[162:165], v[170:173], v[118:121]
	v_mfma_f32_16x16x32_bf16 v[106:109], v[154:157], v[178:181], v[106:109]
	v_mfma_f32_16x16x32_bf16 v[102:105], v[162:165], v[178:181], v[102:105]
	v_mfma_f32_16x16x32_bf16 v[84:87], v[154:157], v[198:201], v[84:87]
	v_mfma_f32_16x16x32_bf16 v[80:83], v[162:165], v[198:201], v[80:83]
	v_mfma_f32_16x16x32_bf16 v[68:71], v[154:157], v[206:209], v[68:71]
	v_mfma_f32_16x16x32_bf16 v[64:67], v[162:165], v[206:209], v[64:67]
	s_barrier
	s_setprio 0
	s_add_i32 s77, s77, s61
	v_lshl_add_u64 v[210:211], s[56:57], 0, v[96:97]
	s_mov_b32 m0, s77
	ds_read_b128 v[166:169], v236 offset:16384
	ds_read_b128 v[170:173], v236 offset:17408
	ds_read_b128 v[174:177], v236 offset:18432
	ds_read_b128 v[178:181], v236 offset:19456
	ds_read_b128 v[194:197], v236 offset:20480
	ds_read_b128 v[198:201], v236 offset:21504
	ds_read_b128 v[202:205], v236 offset:22528
	ds_read_b128 v[206:209], v236 offset:23552
	global_load_lds_dwordx4 v[210:211], off
	s_add_i32 m0, s77, 0x2000
	s_add_u32 s78, s56, 0x80000
	v_lshl_add_u64 v[212:213], s[56:57], 0, v[98:99]
	s_addc_u32 s79, s57, 0
	s_add_i32 s77, s80, s61
	global_load_lds_dwordx4 v[212:213], off
	v_lshl_add_u64 v[214:215], s[78:79], 0, v[96:97]
	s_mov_b32 m0, s77
	v_lshl_add_u64 v[216:217], s[58:59], 0, v[186:187]
	global_load_lds_dwordx4 v[214:215], off
	v_lshl_add_u64 v[214:215], s[78:79], 0, v[98:99]
	s_add_i32 m0, s77, 0x2000
	s_nop 0
	global_load_lds_dwordx4 v[214:215], off
	v_lshl_add_u64 v[214:215], s[58:59], 0, v[188:189]
	s_mov_b32 m0, s62
	s_nop 0
	global_load_lds_dwordx4 v[214:215], off
	s_mov_b32 m0, s63
	s_nop 0
	global_load_lds_dwordx4 v[216:217], off
	s_waitcnt vmcnt(8)
	s_waitcnt lgkmcnt(0)
	s_setprio 1
	s_barrier
; #define PG8_STAGE(bufoff, gbase, voff) do { _Pragma("unroll") for (int _i = 0; _i < 2; ++_i) \
;         __builtin_amdgcn_global_load_lds((const unsigned*)((const char*)(gbase) + (voff)[_i]), (PG8_LAS unsigned*)(lds + (bufoff) + ldsw + _i * 8192), 16, 0, 0); } while (0)
; #define PG8_LDA(dst, b, h) do { _Pragma("unroll") for (int m = 0; m < 4; ++m) _Pragma("unroll") for (int k = 0; k < 2; ++k) dst[m][k] = *(const PG8_LAS bf16x8*)(lds + PG8_SA(b, h) + aoff + m * 2048 + k * 1024); } while (0)
; #define PG8_LDB(dst, b, h) do { _Pragma("unroll") for (int n = 0; n < 2; ++n) _Pragma("unroll") for (int k = 0; k < 2; ++k) dst[n][k] = *(const PG8_LAS bf16x8*)(lds + PG8_SB(b, h) + boff + n * 2048 + k * 1024); } while (0)
; #define PG8_MMA(ai, bj, At, Bt) do { __builtin_amdgcn_s_setprio(1); _Pragma("unroll") for (int m = 0; m < 4; ++m) _Pragma("unroll") for (int n = 0; n < 2; ++n) _Pragma("unroll") for (int k = 0; k < 2; ++k) \
;         acc[ai][bj][m][n] = __builtin_amdgcn_mfma_f32_16x16x32_bf16(Bt[n][k], At[m][k], acc[ai][bj][m][n], 0, 0, 0); __builtin_amdgcn_s_setprio(0); } while (0)
; #define PG8_WAIT_V(n) asm volatile("s_waitcnt vmcnt(" #n ")" ::: "memory")
; #define PG8_WAIT_L(n) asm volatile("s_waitcnt lgkmcnt(" #n ")" ::: "memory")
; #define PG8_BAR __builtin_amdgcn_s_barrier()
; #define PG8_SCHED __builtin_amdgcn_sched_barrier(0)
; template <class Epi, class Sched, bool ALIGN_EPI = false, bool SP2 = false>
; __device__ __forceinline__ void gemm_phase(PG8_LAS unsigned char* lds, const Gemm g, const Sched& S, const Epi& E, const int tid) {
;     ...
;             PG8_WAIT_V(8); PG8_WAIT_L(0); PG8_BAR; PG8_MMA(0, 0, At, B0); PG8_MMA(0, 1, At, B1); PG8_BAR; PG8_SCHED;
;             PG8_LDA(At, 0, 1); PG8_STAGE(PG8_SB(0, 0), b2, voffB); PG8_STAGE(PG8_SB(0, 1), b2 + hstep, voffB); PG8_STAGE(PG8_SA(0, 0), a2, voffA);
;             PG8_WAIT_V(8); PG8_WAIT_L(0); PG8_BAR; PG8_MMA(1, 0, At, B0); PG8_MMA(1, 1, At, B1); PG8_BAR; PG8_SCHED;
;             PG8_LDB(B0, 1, 0); PG8_LDB(B1, 1, 1); PG8_SCHED; PG8_LDA(At, 1, 0); PG8_STAGE(PG8_SA(0, 1), a2 + hstep, voffA);
;             PG8_WAIT_V(8); PG8_WAIT_L(0); PG8_BAR; PG8_MMA(0, 0, At, B0); PG8_MMA(0, 1, At, B1); PG8_BAR; PG8_SCHED;
	v_mfma_f32_16x16x32_bf16 v[60:63], v[126:129], v[166:169], v[60:63]
	v_mfma_f32_16x16x32_bf16 v[56:59], v[142:145], v[166:169], v[56:59]
	v_mfma_f32_16x16x32_bf16 v[44:47], v[126:129], v[174:177], v[44:47]
	v_mfma_f32_16x16x32_bf16 v[40:43], v[142:145], v[174:177], v[40:43]
	v_mfma_f32_16x16x32_bf16 v[28:31], v[126:129], v[194:197], v[28:31]
	v_mfma_f32_16x16x32_bf16 v[24:27], v[142:145], v[194:197], v[24:27]
	v_mfma_f32_16x16x32_bf16 v[12:15], v[126:129], v[202:205], v[12:15]
	v_mfma_f32_16x16x32_bf16 v[8:11], v[142:145], v[202:205], v[8:11]
	v_mfma_f32_16x16x32_bf16 v[60:63], v[130:133], v[170:173], v[60:63]
	v_mfma_f32_16x16x32_bf16 v[56:59], v[146:149], v[170:173], v[56:59]
	v_mfma_f32_16x16x32_bf16 v[44:47], v[130:133], v[178:181], v[44:47]
	v_mfma_f32_16x16x32_bf16 v[40:43], v[146:149], v[178:181], v[40:43]
	v_mfma_f32_16x16x32_bf16 v[28:31], v[130:133], v[198:201], v[28:31]
	v_mfma_f32_16x16x32_bf16 v[24:27], v[146:149], v[198:201], v[24:27]
	v_mfma_f32_16x16x32_bf16 v[12:15], v[130:133], v[206:209], v[12:15]
	v_mfma_f32_16x16x32_bf16 v[8:11], v[146:149], v[206:209], v[8:11]
	v_mfma_f32_16x16x32_bf16 v[52:55], v[150:153], v[166:169], v[52:55]
	v_mfma_f32_16x16x32_bf16 v[48:51], v[158:161], v[166:169], v[48:51]
	v_mfma_f32_16x16x32_bf16 v[36:39], v[150:153], v[174:177], v[36:39]
	v_mfma_f32_16x16x32_bf16 v[32:35], v[158:161], v[174:177], v[32:35]
	v_mfma_f32_16x16x32_bf16 v[20:23], v[150:153], v[194:197], v[20:23]
	v_mfma_f32_16x16x32_bf16 v[16:19], v[158:161], v[194:197], v[16:19]
	v_mfma_f32_16x16x32_bf16 v[4:7], v[150:153], v[202:205], v[4:7]
	v_mfma_f32_16x16x32_bf16 v[0:3], v[158:161], v[202:205], v[0:3]
	v_mfma_f32_16x16x32_bf16 v[52:55], v[154:157], v[170:173], v[52:55]
	v_mfma_f32_16x16x32_bf16 v[48:51], v[162:165], v[170:173], v[48:51]
	v_mfma_f32_16x16x32_bf16 v[36:39], v[154:157], v[178:181], v[36:39]
	v_mfma_f32_16x16x32_bf16 v[32:35], v[162:165], v[178:181], v[32:35]
	v_mfma_f32_16x16x32_bf16 v[20:23], v[154:157], v[198:201], v[20:23]
	v_mfma_f32_16x16x32_bf16 v[16:19], v[162:165], v[198:201], v[16:19]
	v_mfma_f32_16x16x32_bf16 v[4:7], v[154:157], v[206:209], v[4:7]
	v_mfma_f32_16x16x32_bf16 v[0:3], v[162:165], v[206:209], v[0:3]
	s_barrier
	s_setprio 0
	s_add_i32 s77, 0, 0x18000
	s_add_i32 s78, 0, 0x1c000
	v_add_u32_e32 v146, s77, v233
	v_add_u32_e32 v162, s78, v233
	ds_read_b128 v[126:129], v146
	ds_read_b128 v[130:133], v146 offset:1024
	ds_read_b128 v[142:145], v146 offset:2048
	ds_read_b128 v[146:149], v146 offset:3072
	ds_read_b128 v[150:153], v162
	ds_read_b128 v[154:157], v162 offset:1024
	ds_read_b128 v[158:161], v162 offset:2048
	ds_read_b128 v[162:165], v162 offset:3072
	s_add_u32 s58, s58, 0x80000
	s_addc_u32 s59, s59, 0
	s_mov_b32 m0, s64
	v_lshl_add_u64 v[218:219], s[58:59], 0, v[188:189]
	ds_read_b128 v[166:169], v236 offset:32768
	ds_read_b128 v[170:173], v236 offset:33792
	ds_read_b128 v[174:177], v236 offset:34816
	ds_read_b128 v[178:181], v236 offset:35840
	ds_read_b128 v[194:197], v236 offset:36864
	ds_read_b128 v[198:201], v236 offset:37888
	ds_read_b128 v[202:205], v236 offset:38912
	ds_read_b128 v[206:209], v236 offset:39936
	global_load_lds_dwordx4 v[218:219], off
	v_lshl_add_u64 v[218:219], s[58:59], 0, v[186:187]
	s_mov_b32 m0, s65
	s_nop 0
	global_load_lds_dwordx4 v[218:219], off
	s_waitcnt vmcnt(8)
	s_waitcnt lgkmcnt(0)
	s_setprio 1
	s_barrier
	v_mfma_f32_16x16x32_bf16 v[138:141], v[126:129], v[166:169], v[138:141]
	v_mfma_f32_16x16x32_bf16 v[134:137], v[142:145], v[166:169], v[134:137]
	v_mfma_f32_16x16x32_bf16 v[114:117], v[126:129], v[174:177], v[114:117]
	v_mfma_f32_16x16x32_bf16 v[110:113], v[142:145], v[174:177], v[110:113]
	v_mfma_f32_16x16x32_bf16 v[92:95], v[126:129], v[194:197], v[92:95]
	v_mfma_f32_16x16x32_bf16 v[88:91], v[142:145], v[194:197], v[88:91]
	v_mfma_f32_16x16x32_bf16 v[76:79], v[126:129], v[202:205], v[76:79]
	v_mfma_f32_16x16x32_bf16 v[72:75], v[142:145], v[202:205], v[72:75]
	v_mfma_f32_16x16x32_bf16 v[138:141], v[130:133], v[170:173], v[138:141]
	v_mfma_f32_16x16x32_bf16 v[134:137], v[146:149], v[170:173], v[134:137]
	v_mfma_f32_16x16x32_bf16 v[114:117], v[130:133], v[178:181], v[114:117]
	v_mfma_f32_16x16x32_bf16 v[110:113], v[146:149], v[178:181], v[110:113]
	v_mfma_f32_16x16x32_bf16 v[92:95], v[130:133], v[198:201], v[92:95]
	v_mfma_f32_16x16x32_bf16 v[88:91], v[146:149], v[198:201], v[88:91]
	v_mfma_f32_16x16x32_bf16 v[76:79], v[130:133], v[206:209], v[76:79]
	v_mfma_f32_16x16x32_bf16 v[72:75], v[146:149], v[206:209], v[72:75]
	v_mfma_f32_16x16x32_bf16 v[122:125], v[150:153], v[166:169], v[122:125]
	v_mfma_f32_16x16x32_bf16 v[118:121], v[158:161], v[166:169], v[118:121]
	v_mfma_f32_16x16x32_bf16 v[106:109], v[150:153], v[174:177], v[106:109]
	v_mfma_f32_16x16x32_bf16 v[102:105], v[158:161], v[174:177], v[102:105]
	v_mfma_f32_16x16x32_bf16 v[84:87], v[150:153], v[194:197], v[84:87]
	v_mfma_f32_16x16x32_bf16 v[80:83], v[158:161], v[194:197], v[80:83]
	v_mfma_f32_16x16x32_bf16 v[68:71], v[150:153], v[202:205], v[68:71]
	v_mfma_f32_16x16x32_bf16 v[64:67], v[158:161], v[202:205], v[64:67]
	v_mfma_f32_16x16x32_bf16 v[122:125], v[154:157], v[170:173], v[122:125]
	v_mfma_f32_16x16x32_bf16 v[118:121], v[162:165], v[170:173], v[118:121]
	v_mfma_f32_16x16x32_bf16 v[106:109], v[154:157], v[178:181], v[106:109]
	v_mfma_f32_16x16x32_bf16 v[102:105], v[162:165], v[178:181], v[102:105]
	v_mfma_f32_16x16x32_bf16 v[84:87], v[154:157], v[198:201], v[84:87]
	v_mfma_f32_16x16x32_bf16 v[80:83], v[162:165], v[198:201], v[80:83]
	v_mfma_f32_16x16x32_bf16 v[68:71], v[154:157], v[206:209], v[68:71]
	v_mfma_f32_16x16x32_bf16 v[64:67], v[162:165], v[206:209], v[64:67]
	s_barrier
; #define PG8_GAS __attribute__((address_space(1)))
; #define PG8_STAGE(bufoff, gbase, voff) do { _Pragma("unroll") for (int _i = 0; _i < 2; ++_i) \
;         __builtin_amdgcn_global_load_lds((const unsigned*)((const char*)(gbase) + (voff)[_i]), (PG8_LAS unsigned*)(lds + (bufoff) + ldsw + _i * 8192), 16, 0, 0); } while (0)
; #define PG8_LDA(dst, b, h) do { _Pragma("unroll") for (int m = 0; m < 4; ++m) _Pragma("unroll") for (int k = 0; k < 2; ++k) dst[m][k] = *(const PG8_LAS bf16x8*)(lds + PG8_SA(b, h) + aoff + m * 2048 + k * 1024); } while (0)
; #define PG8_MMA(ai, bj, At, Bt) do { __builtin_amdgcn_s_setprio(1); _Pragma("unroll") for (int m = 0; m < 4; ++m) _Pragma("unroll") for (int n = 0; n < 2; ++n) _Pragma("unroll") for (int k = 0; k < 2; ++k) \
;         acc[ai][bj][m][n] = __builtin_amdgcn_mfma_f32_16x16x32_bf16(Bt[n][k], At[m][k], acc[ai][bj][m][n], 0, 0, 0); __builtin_amdgcn_s_setprio(0); } while (0)
; #define PG8_WAIT_V(n) asm volatile("s_waitcnt vmcnt(" #n ")" ::: "memory")
; #define PG8_BAR __builtin_amdgcn_s_barrier()
;     __device__ __forceinline__ void operator()(const f32x4 (&acc)[2][2][4][2], const Unit& u, int wr, int wc, int fr, int fq) const {
;         const int row0 = u.pm * BM + wr * 64 + fr, col0 = u.pn * BM + wc * 32 + 8 * fq, lcol = u.pn * BM + (wc * 4 + fq) * 16;
; #pragma unroll
;         for (int ai = 0; ai < 2; ++ai) {
;             u32x4 L4[4], H4[4][2];
; #pragma unroll
;             for (int m = 0; m < 4; ++m) {
;                 const int row = row0 + ai * HALF + m * 16; const size_t off = (size_t)row * 2048 + col0, loff = (size_t)row * 2048 + lcol;
;                 L4[m] = *(const PG8_GAS u32x4*)(lin + loff); H4[m][0] = *(const PG8_GAS u32x4*)(hin + off); H4[m][1] = *(const PG8_GAS u32x4*)(hin + off + HALF);
;             }
; template <class Epi, class Sched, bool ALIGN_EPI = false, bool SP2 = false>
; __device__ __forceinline__ void gemm_phase(PG8_LAS unsigned char* lds, const Gemm g, const Sched& S, const Epi& E, const int tid) {
;     ...
;             PG8_WAIT_V(8); PG8_WAIT_L(0); PG8_BAR; PG8_MMA(0, 0, At, B0); PG8_MMA(0, 1, At, B1); PG8_BAR; PG8_SCHED;
;             PG8_LDA(At, 1, 1); PG8_STAGE(PG8_SB(1, 0), b3, voffB); PG8_STAGE(PG8_SB(1, 1), b3 + hstep, voffB); PG8_STAGE(PG8_SA(1, 0), a3, voffA);
;             PG8_WAIT_V(8); PG8_WAIT_L(0); PG8_BAR; PG8_MMA(1, 0, At, B0); PG8_MMA(1, 1, At, B1); PG8_BAR; PG8_SCHED;
	s_setprio 0
	s_add_i32 s58, s77, s61
	v_lshl_add_u64 v[210:211], v[210:211], 0, s[28:29]
	s_mov_b32 m0, s58
	ds_read_b128 v[166:169], v236 offset:49152
	ds_read_b128 v[170:173], v236 offset:50176
	ds_read_b128 v[174:177], v236 offset:51200
	ds_read_b128 v[178:181], v236 offset:52224
	ds_read_b128 v[194:197], v236 offset:53248
	ds_read_b128 v[198:201], v236 offset:54272
	ds_read_b128 v[202:205], v236 offset:55296
	ds_read_b128 v[206:209], v236 offset:56320
	global_load_lds_dwordx4 v[210:211], off
	s_add_i32 m0, s58, 0x2000
	s_add_u32 s56, s56, 0x80080
	v_lshl_add_u64 v[210:211], v[212:213], 0, s[28:29]
	s_addc_u32 s57, s57, 0
	s_add_i32 s58, s78, s61
	global_load_lds_dwordx4 v[210:211], off
	v_lshl_add_u64 v[210:211], s[56:57], 0, v[96:97]
	s_mov_b32 m0, s58
	s_nop 0
	global_load_lds_dwordx4 v[210:211], off
	v_lshl_add_u64 v[210:211], s[56:57], 0, v[98:99]
	s_add_i32 m0, s58, 0x2000
	s_nop 0
	global_load_lds_dwordx4 v[210:211], off
	v_lshl_add_u64 v[210:211], v[214:215], 0, s[28:29]
	s_mov_b32 m0, s66
	s_nop 0
	global_load_lds_dwordx4 v[210:211], off
	v_lshl_add_u64 v[210:211], v[216:217], 0, s[28:29]
	s_mov_b32 m0, s67
	s_nop 0
	global_load_lds_dwordx4 v[210:211], off
	s_waitcnt vmcnt(8)
	s_waitcnt lgkmcnt(0)
	s_setprio 1
	s_barrier
	v_mfma_f32_16x16x32_bf16 v[60:63], v[126:129], v[166:169], v[60:63]
	v_mfma_f32_16x16x32_bf16 v[56:59], v[142:145], v[166:169], v[56:59]
	v_mfma_f32_16x16x32_bf16 v[44:47], v[126:129], v[174:177], v[44:47]
	v_mfma_f32_16x16x32_bf16 v[40:43], v[142:145], v[174:177], v[40:43]
	v_mfma_f32_16x16x32_bf16 v[28:31], v[126:129], v[194:197], v[28:31]
	v_mfma_f32_16x16x32_bf16 v[24:27], v[142:145], v[194:197], v[24:27]
	v_mfma_f32_16x16x32_bf16 v[12:15], v[126:129], v[202:205], v[12:15]
	v_mfma_f32_16x16x32_bf16 v[8:11], v[142:145], v[202:205], v[8:11]
	v_mfma_f32_16x16x32_bf16 v[60:63], v[130:133], v[170:173], v[60:63]
	v_mfma_f32_16x16x32_bf16 v[56:59], v[146:149], v[170:173], v[56:59]
	v_mfma_f32_16x16x32_bf16 v[44:47], v[130:133], v[178:181], v[44:47]
	v_mfma_f32_16x16x32_bf16 v[40:43], v[146:149], v[178:181], v[40:43]
	v_mfma_f32_16x16x32_bf16 v[28:31], v[130:133], v[198:201], v[28:31]
	v_mfma_f32_16x16x32_bf16 v[24:27], v[146:149], v[198:201], v[24:27]
	v_mfma_f32_16x16x32_bf16 v[12:15], v[130:133], v[206:209], v[12:15]
	v_mfma_f32_16x16x32_bf16 v[8:11], v[146:149], v[206:209], v[8:11]
	v_mfma_f32_16x16x32_bf16 v[52:55], v[150:153], v[166:169], v[52:55]
	v_mfma_f32_16x16x32_bf16 v[48:51], v[158:161], v[166:169], v[48:51]
	v_mfma_f32_16x16x32_bf16 v[36:39], v[150:153], v[174:177], v[36:39]
	v_mfma_f32_16x16x32_bf16 v[32:35], v[158:161], v[174:177], v[32:35]
	v_mfma_f32_16x16x32_bf16 v[20:23], v[150:153], v[194:197], v[20:23]
	v_mfma_f32_16x16x32_bf16 v[16:19], v[158:161], v[194:197], v[16:19]
	v_mfma_f32_16x16x32_bf16 v[4:7], v[150:153], v[202:205], v[4:7]
	v_mfma_f32_16x16x32_bf16 v[0:3], v[158:161], v[202:205], v[0:3]
	v_mfma_f32_16x16x32_bf16 v[52:55], v[154:157], v[170:173], v[52:55]
	v_mfma_f32_16x16x32_bf16 v[48:51], v[162:165], v[170:173], v[48:51]
	v_mfma_f32_16x16x32_bf16 v[36:39], v[154:157], v[178:181], v[36:39]
	v_mfma_f32_16x16x32_bf16 v[32:35], v[162:165], v[178:181], v[32:35]
	v_mfma_f32_16x16x32_bf16 v[20:23], v[154:157], v[198:201], v[20:23]
	v_mfma_f32_16x16x32_bf16 v[16:19], v[162:165], v[198:201], v[16:19]
	v_mfma_f32_16x16x32_bf16 v[4:7], v[154:157], v[206:209], v[4:7]
	v_mfma_f32_16x16x32_bf16 v[0:3], v[162:165], v[206:209], v[0:3]
	s_barrier
	s_setprio 0
	s_add_i32 s76, s76, 2
	s_add_u32 s73, s73, 0x100
	s_addc_u32 s75, s75, 0
	s_add_u32 s54, s54, 0x100
	s_addc_u32 s55, s55, 0
	s_cmp_gt_u32 s76, 29
	s_cbranch_scc0 .LBB0_1199
	v_and_b32_e32 v127, 64, v228
	v_xor_b32_e32 v126, 16, v228
	v_add_u32_e32 v127, 64, v127
	v_cmp_lt_i32_e32 vcc, v126, v127
	s_lshl_b32 s47, s69, 8
	v_lshl_add_u32 v198, s70, 8, v101
	v_cndmask_b32_e32 v126, v228, v126, vcc
	v_or_b32_e32 v194, s47, v235
	v_lshlrev_b32_e32 v238, 2, v126
	v_xor_b32_e32 v126, 32, v228
	v_or_b32_e32 v196, s47, v234
	v_ashrrev_i32_e32 v195, 31, v194
	v_cmp_lt_i32_e32 vcc, v126, v127
	v_ashrrev_i32_e32 v199, 31, v198
	v_ashrrev_i32_e32 v197, 31, v196
	v_cndmask_b32_e32 v126, v228, v126, vcc
	v_lshl_add_u64 v[202:203], s[34:35], 0, v[194:195]
	v_lshlrev_b64 v[216:217], 11, v[198:199]
	v_lshlrev_b32_e32 v237, 2, v126
	v_lshlrev_b64 v[218:219], 1, v[196:197]
	v_lshl_add_u64 v[126:127], v[202:203], 0, v[216:217]
	v_lshl_add_u64 v[200:201], s[30:31], 0, v[218:219]
	global_load_dwordx4 v[170:173], v[126:127], off
	v_lshlrev_b64 v[220:221], 12, v[198:199]
	v_lshl_add_u64 v[126:127], v[200:201], 0, v[220:221]
	global_load_dwordx4 v[178:181], v[126:127], off
	global_load_dwordx4 v[174:177], v[126:127], off offset:256
	v_or_b32_e32 v212, 16, v198
	v_ashrrev_i32_e32 v213, 31, v212
	v_lshlrev_b64 v[214:215], 11, v[212:213]
	v_lshl_add_u64 v[126:127], v[202:203], 0, v[214:215]
	v_or_b32_e32 v208, 32, v198
	global_load_dwordx4 v[158:161], v[126:127], off
	v_lshlrev_b64 v[126:127], 12, v[212:213]
	v_ashrrev_i32_e32 v209, 31, v208
	v_lshl_add_u64 v[126:127], v[200:201], 0, v[126:127]
	v_lshlrev_b64 v[210:211], 11, v[208:209]
	global_load_dwordx4 v[166:169], v[126:127], off
	global_load_dwordx4 v[162:165], v[126:127], off offset:256
	v_lshl_add_u64 v[126:127], v[202:203], 0, v[210:211]
	v_or_b32_e32 v204, 48, v198
	global_load_dwordx4 v[146:149], v[126:127], off
	v_lshlrev_b64 v[126:127], 12, v[208:209]
	v_ashrrev_i32_e32 v205, 31, v204
	v_lshl_add_u64 v[126:127], v[200:201], 0, v[126:127]
	v_lshlrev_b64 v[206:207], 11, v[204:205]
	v_lshlrev_b64 v[130:131], 12, v[204:205]
	global_load_dwordx4 v[154:157], v[126:127], off
	global_load_dwordx4 v[150:153], v[126:127], off offset:256
	v_lshl_add_u64 v[126:127], v[202:203], 0, v[206:207]
	v_lshl_add_u64 v[130:131], v[200:201], 0, v[130:131]
	global_load_dwordx4 v[126:129], v[126:127], off
	s_nop 0
	global_load_dwordx4 v[142:145], v[130:131], off
	s_nop 0
	global_load_dwordx4 v[130:133], v[130:131], off offset:256
	v_mov_b32_e32 v225, v134
	v_mov_b32_e32 v243, v136
	v_mov_b32_e32 v242, v140
	s_waitcnt vmcnt(0)
; #define PG8_GAS __attribute__((address_space(1)))
; __device__ __forceinline__ float e_x24(unsigned h16, unsigned l8) { return __uint_as_float(((h16 - (l8 >> 7)) << 16) | (l8 << 8)); }
;     __device__ __forceinline__ void operator()(const f32x4 (&acc)[2][2][4][2], const Unit& u, int wr, int wc, int fr, int fq) const {
;     ...
;             for (int m = 0; m < 4; ++m) {
;                 const int row = row0 + ai * HALF + m * 16; const size_t off = (size_t)row * 2048 + col0, loff = (size_t)row * 2048 + lcol; float ss = 0.f;
;                 const u32x4 l4 = L4[m];
;                 u32x4 lo4;
; #pragma unroll
;                 for (int bj = 0; bj < 2; ++bj) {
;                     const u32x4 h4 = H4[m][bj];
;                     u32x4 ho;
; #pragma unroll
;                     for (int j = 0; j < 4; ++j) {
;                         const unsigned lw = l4[2 * bj + (j >> 1)], lb0 = (lw >> (16 * (j & 1))) & 0xffu, lb1 = (lw >> (16 * (j & 1) + 8)) & 0xffu;
;                         const float x0 = e_x24(h4[j] & 0xffffu, lb0) + acc[ai][bj][m][j >> 1][2 * (j & 1)] * scale, x1 = e_x24(h4[j] >> 16, lb1) + acc[ai][bj][m][j >> 1][2 * (j & 1) + 1] * scale;
;                         const unsigned b0 = __float_as_uint(x0), b1 = __float_as_uint(x1);
;                         ho[j] = ((b0 + 0x8000u) >> 16) | ((b1 + 0x8000u) & 0xffff0000u);
;                         const unsigned nb = ((b0 >> 8) & 0xffu) | (b1 & 0xff00u);
;                         if ((j & 1) == 0) lo4[2 * bj + (j >> 1)] = nb; else lo4[2 * bj + (j >> 1)] |= nb << 16;
;                         ss += x0 * x0 + x1 * x1;
;                     }
;                     *(PG8_GAS u32x4*)(hout + off + bj * HALF) = ho;
	v_lshrrev_b32_sdwa v182, v229, v171 dst_sel:DWORD dst_unused:UNUSED_PAD src0_sel:DWORD src1_sel:BYTE_0
	v_lshrrev_b32_sdwa v183, v229, v170 dst_sel:DWORD dst_unused:UNUSED_PAD src0_sel:DWORD src1_sel:BYTE_0
	v_sub_u32_sdwa v183, v178, v183 dst_sel:WORD_1 dst_unused:UNUSED_PAD src0_sel:DWORD src1_sel:DWORD
	v_sub_u32_sdwa v182, v180, v182 dst_sel:WORD_1 dst_unused:UNUSED_PAD src0_sel:DWORD src1_sel:DWORD
	v_lshlrev_b32_sdwa v222, v230, v171 dst_sel:DWORD dst_unused:UNUSED_PAD src0_sel:DWORD src1_sel:BYTE_0
	v_lshlrev_b32_sdwa v224, v230, v170 dst_sel:DWORD dst_unused:UNUSED_PAD src0_sel:DWORD src1_sel:BYTE_0
	v_or_b32_e32 v223, v182, v222
	v_or_b32_e32 v222, v183, v224
	v_mov_b32_e32 v224, v138
	v_pk_add_f32 v[222:223], v[224:225], v[222:223]
	v_lshlrev_b32_e32 v182, 1, v170
	v_add_u32_e32 v134, 0x8000, v222
	v_lshrrev_b32_e32 v138, 16, v134
	v_lshlrev_b32_e32 v134, 1, v171
	v_and_b32_e32 v134, 0x10000, v134
	v_and_b32_e32 v182, 0x10000, v182
	v_sub_u32_e32 v134, v180, v134
	v_sub_u32_e32 v178, v178, v182
	v_and_b32_e32 v134, 0xffff0000, v134
	v_and_b32_e32 v178, 0xffff0000, v178
	v_and_b32_e32 v180, 0xff00, v171
	v_and_b32_e32 v182, 0xff00, v170
	v_or_b32_e32 v225, v134, v180
	v_or_b32_e32 v224, v178, v182
	v_mov_b32_e32 v134, v139
	v_pk_add_f32 v[224:225], v[134:135], v[224:225]
	v_and_b32_sdwa v135, v171, s93 dst_sel:DWORD dst_unused:UNUSED_PAD src0_sel:WORD_1 src1_sel:DWORD
	v_and_b32_sdwa v178, v170, s93 dst_sel:DWORD dst_unused:UNUSED_PAD src0_sel:WORD_1 src1_sel:DWORD
	v_lshlrev_b32_sdwa v182, v231, v170 dst_sel:DWORD dst_unused:UNUSED_PAD src0_sel:DWORD src1_sel:BYTE_3
	v_lshlrev_b32_sdwa v136, v231, v171 dst_sel:DWORD dst_unused:UNUSED_PAD src0_sel:DWORD src1_sel:BYTE_3
	v_lshrrev_b32_e32 v180, 7, v178
	v_lshrrev_b32_e32 v183, 7, v135
	v_and_b32_e32 v136, 0x10000, v136
	v_and_b32_e32 v140, 0x10000, v182
	v_sub_u32_sdwa v180, v179, v180 dst_sel:WORD_1 dst_unused:UNUSED_PAD src0_sel:DWORD src1_sel:DWORD
	v_sub_u32_sdwa v183, v181, v183 dst_sel:WORD_1 dst_unused:UNUSED_PAD src0_sel:DWORD src1_sel:DWORD
	v_lshlrev_b32_e32 v135, 8, v135
	v_lshlrev_b32_e32 v178, 8, v178
	v_sub_u32_e32 v136, v181, v136
	v_sub_u32_e32 v140, v179, v140
	v_or_b32_e32 v241, v183, v135
	v_or_b32_e32 v240, v180, v178
	v_and_b32_e32 v136, 0xffff0000, v136
	v_and_b32_e32 v140, 0xffff0000, v140
	v_lshlrev_b32_sdwa v171, v230, v171 dst_sel:DWORD dst_unused:UNUSED_PAD src0_sel:DWORD src1_sel:BYTE_3
	v_lshlrev_b32_sdwa v170, v230, v170 dst_sel:DWORD dst_unused:UNUSED_PAD src0_sel:DWORD src1_sel:BYTE_3
	v_pk_add_f32 v[240:241], v[242:243], v[240:241]
	v_or_b32_e32 v171, v136, v171
	v_or_b32_e32 v170, v140, v170
	v_mov_b32_e32 v136, v141
	v_add_u32_e32 v135, 0x8000, v240
	v_pk_add_f32 v[140:141], v[136:137], v[170:171]
	v_lshrrev_b32_e32 v135, 16, v135
	v_add_u32_e32 v136, 0x8000, v140
	v_and_or_b32 v135, v136, s90, v135
	v_pk_mul_f32 v[136:137], v[140:141], v[140:141]
	v_add_u32_e32 v178, 0x8000, v141
	v_pk_fma_f32 v[170:171], v[240:241], v[240:241], v[136:137]
	v_add_u32_e32 v136, 0x8000, v223
	v_lshrrev_b32_e32 v136, 16, v136
	v_add_u32_e32 v137, 0x8000, v225
	v_and_or_b32 v136, v137, s90, v136
	v_add_u32_e32 v137, 0x8000, v241
	v_lshrrev_b32_e32 v137, 16, v137
	v_add_u32_e32 v134, 0x8000, v224
	v_and_or_b32 v137, v178, s90, v137
	v_lshl_add_u64 v[178:179], s[30:31], 0, v[220:221]
	v_and_or_b32 v134, v134, s90, v138
	v_lshl_add_u64 v[178:179], v[178:179], 0, v[218:219]
	global_store_dwordx4 v[178:179], v[134:137], off
	v_lshlrev_b32_sdwa v182, v231, v172 dst_sel:DWORD dst_unused:UNUSED_PAD src0_sel:DWORD src1_sel:BYTE_3
	v_mov_b32_e32 v219, v120
	v_lshrrev_b32_sdwa v134, v229, v173 dst_sel:DWORD dst_unused:UNUSED_PAD src0_sel:DWORD src1_sel:BYTE_0
	v_lshrrev_b32_sdwa v135, v229, v172 dst_sel:DWORD dst_unused:UNUSED_PAD src0_sel:DWORD src1_sel:BYTE_0
	v_sub_u32_sdwa v136, v174, v135 dst_sel:WORD_1 dst_unused:UNUSED_PAD src0_sel:DWORD src1_sel:DWORD
	v_sub_u32_sdwa v134, v176, v134 dst_sel:WORD_1 dst_unused:UNUSED_PAD src0_sel:DWORD src1_sel:DWORD
	v_lshlrev_b32_sdwa v135, v230, v173 dst_sel:DWORD dst_unused:UNUSED_PAD src0_sel:DWORD src1_sel:BYTE_0
	v_lshlrev_b32_sdwa v137, v230, v172 dst_sel:DWORD dst_unused:UNUSED_PAD src0_sel:DWORD src1_sel:BYTE_0
	v_or_b32_e32 v135, v134, v135
	v_or_b32_e32 v134, v136, v137
	v_mov_b32_e32 v136, v122
	v_mov_b32_e32 v137, v118
	v_pk_add_f32 v[134:135], v[136:137], v[134:135]
	v_lshlrev_b32_e32 v122, 1, v172
; #define PG8_GAS __attribute__((address_space(1)))
; __device__ __forceinline__ float e_x24(unsigned h16, unsigned l8) { return __uint_as_float(((h16 - (l8 >> 7)) << 16) | (l8 << 8)); }
;     __device__ __forceinline__ void operator()(const f32x4 (&acc)[2][2][4][2], const Unit& u, int wr, int wc, int fr, int fq) const {
;     ...
;                     for (int j = 0; j < 4; ++j) {
;                         const unsigned lw = l4[2 * bj + (j >> 1)], lb0 = (lw >> (16 * (j & 1))) & 0xffu, lb1 = (lw >> (16 * (j & 1) + 8)) & 0xffu;
;                         const float x0 = e_x24(h4[j] & 0xffffu, lb0) + acc[ai][bj][m][j >> 1][2 * (j & 1)] * scale, x1 = e_x24(h4[j] >> 16, lb1) + acc[ai][bj][m][j >> 1][2 * (j & 1) + 1] * scale;
;                         const unsigned b0 = __float_as_uint(x0), b1 = __float_as_uint(x1);
;                         ho[j] = ((b0 + 0x8000u) >> 16) | ((b1 + 0x8000u) & 0xffff0000u);
;                         const unsigned nb = ((b0 >> 8) & 0xffu) | (b1 & 0xff00u);
;                         if ((j & 1) == 0) lo4[2 * bj + (j >> 1)] = nb; else lo4[2 * bj + (j >> 1)] |= nb << 16;
;                         ss += x0 * x0 + x1 * x1;
;                     }
;                     *(PG8_GAS u32x4*)(hout + off + bj * HALF) = ho;
;                 }
;                 *(PG8_GAS u32x4*)(lout + loff) = lo4;
;                 ss += __shfl_xor(ss, 16); ss += __shfl_xor(ss, 32);
;                 if (fq == 0) __hip_atomic_fetch_add((PG8_GAS unsigned long long*)(rowsq_out + row), (unsigned long long)(ss * 16777216.0f + 0.5f), __ATOMIC_RELAXED, __HIP_MEMORY_SCOPE_AGENT);
	v_add_u32_e32 v118, 0x8000, v134
	v_lshrrev_b32_e32 v180, 16, v118
	v_lshlrev_b32_e32 v118, 1, v173
	v_and_b32_e32 v118, 0x10000, v118
	v_and_b32_e32 v122, 0x10000, v122
	v_sub_u32_e32 v118, v176, v118
	v_sub_u32_e32 v122, v174, v122
	v_and_b32_e32 v118, 0xffff0000, v118
	v_and_b32_e32 v122, 0xffff0000, v122
	v_and_b32_e32 v136, 0xff00, v173
	v_and_b32_e32 v174, 0xff00, v172
	v_or_b32_e32 v137, v118, v136
	v_or_b32_e32 v136, v122, v174
	v_mov_b32_e32 v118, v123
	v_pk_add_f32 v[122:123], v[118:119], v[136:137]
	v_and_b32_sdwa v119, v173, s93 dst_sel:DWORD dst_unused:UNUSED_PAD src0_sel:WORD_1 src1_sel:DWORD
	v_add_u32_e32 v118, 0x8000, v122
	v_and_b32_sdwa v174, v172, s93 dst_sel:DWORD dst_unused:UNUSED_PAD src0_sel:WORD_1 src1_sel:DWORD
	v_lshlrev_b32_sdwa v120, v231, v173 dst_sel:DWORD dst_unused:UNUSED_PAD src0_sel:DWORD src1_sel:BYTE_3
	v_and_or_b32 v118, v118, s90, v180
	v_lshrrev_b32_e32 v176, 7, v174
	v_lshrrev_b32_e32 v180, 7, v119
	v_mov_b32_e32 v218, v124
	v_and_b32_e32 v120, 0x10000, v120
	v_and_b32_e32 v124, 0x10000, v182
	v_sub_u32_sdwa v176, v175, v176 dst_sel:WORD_1 dst_unused:UNUSED_PAD src0_sel:DWORD src1_sel:DWORD
	v_sub_u32_sdwa v180, v177, v180 dst_sel:WORD_1 dst_unused:UNUSED_PAD src0_sel:DWORD src1_sel:DWORD
	v_lshlrev_b32_e32 v119, 8, v119
	v_lshlrev_b32_e32 v174, 8, v174
	v_sub_u32_e32 v120, v177, v120
	v_sub_u32_e32 v124, v175, v124
	v_or_b32_e32 v181, v180, v119
	v_or_b32_e32 v180, v176, v174
	v_and_b32_e32 v120, 0xffff0000, v120
	v_and_b32_e32 v124, 0xffff0000, v124
	v_lshlrev_b32_sdwa v173, v230, v173 dst_sel:DWORD dst_unused:UNUSED_PAD src0_sel:DWORD src1_sel:BYTE_3
	v_lshlrev_b32_sdwa v172, v230, v172 dst_sel:DWORD dst_unused:UNUSED_PAD src0_sel:DWORD src1_sel:BYTE_3
	v_pk_add_f32 v[180:181], v[218:219], v[180:181]
	v_or_b32_e32 v173, v120, v173
	v_or_b32_e32 v172, v124, v172
	v_mov_b32_e32 v120, v125
	v_add_u32_e32 v119, 0x8000, v180
	v_pk_add_f32 v[124:125], v[120:121], v[172:173]
	v_lshrrev_b32_e32 v119, 16, v119
	v_add_u32_e32 v120, 0x8000, v124
	v_pk_mul_f32 v[138:139], v[224:225], v[224:225]
	v_pk_mul_f32 v[136:137], v[122:123], v[122:123]
	v_and_or_b32 v119, v120, s90, v119
	v_pk_mul_f32 v[120:121], v[124:125], v[124:125]
	v_pk_fma_f32 v[138:139], v[222:223], v[222:223], v[138:139]
	v_pk_fma_f32 v[136:137], v[134:135], v[134:135], v[136:137]
	v_pk_fma_f32 v[172:173], v[180:181], v[180:181], v[120:121]
	v_add_u32_e32 v120, 0x8000, v135
	v_lshrrev_b32_e32 v134, 8, v134
	v_lshrrev_b32_e32 v120, 16, v120
	v_add_u32_e32 v121, 0x8000, v123
	v_perm_b32 v122, v122, v134, s94
	v_add_f32_e32 v134, v138, v170
	v_and_or_b32 v120, v121, s90, v120
	v_add_u32_e32 v121, 0x8000, v181
	v_add_f32_e32 v134, v139, v134
	v_lshrrev_b32_e32 v121, 16, v121
	v_add_u32_e32 v174, 0x8000, v125
	v_add_f32_e32 v134, v171, v134
	v_and_or_b32 v121, v174, s90, v121
	v_lshrrev_b32_e32 v174, 8, v181
	v_lshrrev_b32_e32 v175, 8, v180
	v_add_f32_e32 v134, v136, v134
	v_lshrrev_b32_e32 v176, 8, v241
	v_lshrrev_b32_e32 v177, 8, v240
	v_perm_b32 v124, v124, v175, s94
	v_perm_b32 v125, v125, v174, s94
	v_lshrrev_b32_e32 v135, 8, v135
	v_lshrrev_b32_e32 v174, 8, v223
	v_lshrrev_b32_e32 v175, 8, v222
	v_add_f32_e32 v134, v172, v134
	v_perm_b32 v140, v140, v177, s94
	v_perm_b32 v141, v141, v176, s94
	v_perm_b32 v175, v224, v175, s94
	v_perm_b32 v174, v225, v174, s94
	v_perm_b32 v123, v123, v135, s94
	v_add_f32_e32 v134, v137, v134
	global_store_dwordx4 v[178:179], v[118:121], off offset:256
	v_lshl_or_b32 v125, v125, 16, v123
	v_lshl_or_b32 v124, v124, 16, v122
	v_lshl_add_u64 v[118:119], s[34:35], 0, v[216:217]
	v_lshl_or_b32 v123, v141, 16, v174
	v_lshl_or_b32 v122, v140, 16, v175
	v_add_f32_e32 v134, v173, v134
	v_lshl_add_u64 v[118:119], v[118:119], 0, v[194:195]
	global_store_dwordx4 v[118:119], v[122:125], off
	ds_bpermute_b32 v118, v238, v134
	s_waitcnt lgkmcnt(0)
	v_add_f32_e32 v118, v134, v118
	ds_bpermute_b32 v119, v237, v118
	s_and_saveexec_b64 s[54:55], s[40:41]
	s_mov_b32 s80, 0x4b800000
	s_cbranch_execz .LBB0_1202
	s_waitcnt lgkmcnt(0)
	v_add_f32_e32 v118, v118, v119
	v_fma_f32 v118, v118, s80, 0.5
	v_trunc_f32_e32 v118, v118
	v_mul_f32_e32 v119, 0x2f800000, v118
	v_floor_f32_e32 v119, v119
	v_fmac_f32_e32 v118, 0xcf800000, v119
	v_cvt_u32_f32_e32 v118, v118
	v_cvt_u32_f32_e32 v119, v119
	v_lshl_add_u64 v[120:121], v[198:199], 3, s[44:45]
	global_atomic_add_x2 v[120:121], v[118:119], off
